# stack on v17: ssq prefetch before FFN-up K-loops + SwiGLU log2e fold + attention K1 prologue hoist + GEMM segment slot cleanup
# speedup vs baseline: 1.0121x; 1.0043x over previous
; #define PG8_STAGE(bufoff, gbase, voff) do { _Pragma("unroll") for (int _i = 0; _i < 2; ++_i) \
;         __builtin_amdgcn_global_load_lds((const unsigned*)((const char*)(gbase) + (voff)[_i]), (LAS unsigned*)(lds + (bufoff) + ldsw + _i * 8192), 16, 0, 0); } while (0)
; #define PG8_LDA(dst, b, h) do { _Pragma("unroll") for (int m = 0; m < 4; ++m) _Pragma("unroll") for (int k = 0; k < 2; ++k) dst[m][k] = *(const LAS bf16x8*)(lds + PG8_SA(b, h) + aoff + m * 2048 + k * 1024); } while (0)
; #define PG8_LDB(dst, b, h) do { _Pragma("unroll") for (int n = 0; n < 2; ++n) _Pragma("unroll") for (int k = 0; k < 2; ++k) dst[n][k] = *(const LAS bf16x8*)(lds + PG8_SB(b, h) + boff + n * 2048 + k * 1024); } while (0)
; #define PG8_BAR __builtin_amdgcn_s_barrier()
; template <class Epi>
; DI void gemm_phase(LAS unsigned char* lds, const int wid, const Gemm g, const Order& S, const Epi& E) {
;     ...
;         const char* nA = has_next ? (const char*)(g.A + (size_t)nxt.g * g.gsA + (size_t)nxt.pm * BM * g.lda) : cA;
;         const char* nB = has_next ? (const char*)(g.Bt + (size_t)nxt.g * g.gsB + (size_t)nxt.pn * BM * g.ldb) : cB;
;         for (int t = 0; t < nt; t += 2) {
;             const bool last = (t == nt - 2);
;             const char* a1 = cA + (size_t)(t + 1) * kstep;
;             const char* a2 = last ? nA : cA + (size_t)(t + 2) * kstep; const char* b2 = last ? nB : cB + (size_t)(t + 2) * kstep;
;             const char* a3 = a2 + kstep; const char* b3 = b2 + kstep;
;             PG8_LDB(B0, 0, 0); PG8_LDB(B1, 0, 1); PG8_SCHED; PG8_LDA(At, 0, 0); PG8_STAGE(PG8_SA(1, 1), a1 + hstepA, voffA);
;             PG8_WAIT_V(8); PG8_WAIT_L(0); PG8_BAR; PG8_MMA(0, 0, At, B0); PG8_MMA(0, 1, At, B1); PG8_BAR; PG8_SCHED;
;             PG8_LDA(At, 0, 1); PG8_STAGE(PG8_SB(0, 0), b2, voffB); PG8_STAGE(PG8_SB(0, 1), b2 + hstepB, voffB); PG8_STAGE(PG8_SA(0, 0), a2, voffA);
;             PG8_WAIT_V(8); PG8_WAIT_L(0); PG8_BAR; PG8_MMA(1, 0, At, B0); PG8_MMA(1, 1, At, B1); PG8_BAR; PG8_SCHED;
; DI float rstd_of(float ssq, float invn) { return __builtin_amdgcn_rsqf(ssq * invn + EPS); }
;     DI void operator()(const Acc& acc, const Unit& u, int wr, int wc, int fr, int fq) const {
;         const int cb = u.pn * 128 + wc * 32 + 8 * fq;
;         EPI_RSTD8(rr, ssq, 1.0f / D)
;         EPI_ROWS(ai, m) { const int row = epi_row(u, ai, wr, m, fr); const float r = rr[ai][m];
.LBB0_227:
	s_ashr_i32 s31, s30, 31
	s_lshl_b64 s[36:37], s[30:31], 19
	s_add_u32 s36, s21, s36
	s_addc_u32 s37, s25, s37
	s_and_b64 s[38:39], s[6:7], exec
	s_cselect_b32 s31, s37, s43
	s_cselect_b32 s59, s36, s42
	s_ashr_i32 s35, s34, 31
	s_lshl_b64 s[38:39], s[34:35], 19
	s_add_u32 s38, s8, s38
	s_addc_u32 s39, s9, s39
	s_and_b64 s[46:47], s[6:7], exec
	s_cselect_b32 s35, s39, s45
	s_cselect_b32 s60, s38, s44
	s_add_u32 s42, s42, 0x40080
	s_addc_u32 s43, s43, 0
	s_add_u32 s61, s44, 0x100
	v_mov_b32_e32 v0, 0
	s_addc_u32 s62, s45, 0
	s_mov_b32 s63, -2
	s_lshl_b32 s74, s40, 8
	s_add_i32 s74, s74, s95
	v_mbcnt_lo_u32_b32 v244, -1, 0
	v_mbcnt_hi_u32_b32 v244, -1, v244
	v_and_or_b32 v244, v244, 15, s74
	v_ashrrev_i32_e32 v245, 31, v244
	v_lshl_add_u64 v[246:247], v[244:245], 2, s[12:13]
	global_load_dword v236, v[246:247], off
	global_load_dword v237, v[246:247], off offset:64
	global_load_dword v238, v[246:247], off offset:128
	global_load_dword v239, v[246:247], off offset:192
	global_load_dword v240, v[246:247], off offset:512
	global_load_dword v241, v[246:247], off offset:576
	global_load_dword v242, v[246:247], off offset:640
	global_load_dword v243, v[246:247], off offset:704
	ds_read_b128 v[164:167], v151
	ds_read_b128 v[168:171], v151 offset:1024
	ds_read_b128 v[172:175], v151 offset:2048
	ds_read_b128 v[176:179], v151 offset:3072
	ds_read_b128 v[180:183], v155
	ds_read_b128 v[184:187], v155 offset:1024
	ds_read_b128 v[188:191], v155 offset:2048
	ds_read_b128 v[192:195], v155 offset:3072
	s_add_u32 s44, s42, 0xfffc0080
	s_addc_u32 s45, s43, -1
	s_cmp_eq_u32 s63, 12
	s_cselect_b32 s47, s31, s45
	s_cselect_b32 s46, s59, s44
	s_cselect_b32 s45, s35, s62
	s_cselect_b32 s44, s60, s61
	v_lshl_add_u64 v[144:145], s[42:43], 0, v[136:137]
	s_add_i32 m0, s27, 0xc000
	ds_read_b128 v[196:199], v159
	ds_read_b128 v[200:203], v159 offset:1024
	ds_read_b128 v[204:207], v159 offset:2048
	ds_read_b128 v[208:211], v159 offset:3072
	ds_read_b128 v[216:219], v159 offset:4096
	ds_read_b128 v[220:223], v159 offset:5120
	ds_read_b128 v[224:227], v159 offset:6144
	ds_read_b128 v[228:231], v159 offset:7168
	global_load_lds_dwordx4 v[144:145], off
	v_lshl_add_u64 v[144:145], s[42:43], 0, v[138:139]
	s_add_i32 m0, s27, 0xe000
	s_nop 0
	global_load_lds_dwordx4 v[144:145], off
	s_waitcnt vmcnt(8)
	s_waitcnt lgkmcnt(0)
	s_barrier
	s_setprio 1
	v_mfma_f32_16x16x32_bf16 v[124:127], v[164:167], v[196:199], 0
	v_mfma_f32_16x16x32_bf16 v[120:123], v[172:175], v[196:199], 0
	v_mfma_f32_16x16x32_bf16 v[108:111], v[164:167], v[204:207], 0
	v_mfma_f32_16x16x32_bf16 v[104:107], v[172:175], v[204:207], 0
	v_mfma_f32_16x16x32_bf16 v[92:95], v[164:167], v[216:219], 0
	v_mfma_f32_16x16x32_bf16 v[88:91], v[172:175], v[216:219], 0
	v_mfma_f32_16x16x32_bf16 v[76:79], v[164:167], v[224:227], 0
	v_mfma_f32_16x16x32_bf16 v[72:75], v[172:175], v[224:227], 0
	v_mfma_f32_16x16x32_bf16 v[124:127], v[168:171], v[200:203], v[124:127]
	v_mfma_f32_16x16x32_bf16 v[120:123], v[176:179], v[200:203], v[120:123]
	v_mfma_f32_16x16x32_bf16 v[108:111], v[168:171], v[208:211], v[108:111]
	v_mfma_f32_16x16x32_bf16 v[104:107], v[176:179], v[208:211], v[104:107]
	v_mfma_f32_16x16x32_bf16 v[92:95], v[168:171], v[220:223], v[92:95]
	v_mfma_f32_16x16x32_bf16 v[88:91], v[176:179], v[220:223], v[88:91]
	v_mfma_f32_16x16x32_bf16 v[76:79], v[168:171], v[228:231], v[76:79]
	v_mfma_f32_16x16x32_bf16 v[72:75], v[176:179], v[228:231], v[72:75]
	v_mfma_f32_16x16x32_bf16 v[116:119], v[180:183], v[196:199], 0
	v_mfma_f32_16x16x32_bf16 v[112:115], v[188:191], v[196:199], 0
	v_mfma_f32_16x16x32_bf16 v[100:103], v[180:183], v[204:207], 0
	v_mfma_f32_16x16x32_bf16 v[96:99], v[188:191], v[204:207], 0
	v_mfma_f32_16x16x32_bf16 v[84:87], v[180:183], v[216:219], 0
	v_mfma_f32_16x16x32_bf16 v[80:83], v[188:191], v[216:219], 0
	v_mfma_f32_16x16x32_bf16 v[68:71], v[180:183], v[224:227], 0
	v_mfma_f32_16x16x32_bf16 v[64:67], v[188:191], v[224:227], 0
	v_mfma_f32_16x16x32_bf16 v[116:119], v[184:187], v[200:203], v[116:119]
	v_mfma_f32_16x16x32_bf16 v[112:115], v[192:195], v[200:203], v[112:115]
	v_mfma_f32_16x16x32_bf16 v[100:103], v[184:187], v[208:211], v[100:103]
	v_mfma_f32_16x16x32_bf16 v[96:99], v[192:195], v[208:211], v[96:99]
	v_mfma_f32_16x16x32_bf16 v[84:87], v[184:187], v[220:223], v[84:87]
	v_mfma_f32_16x16x32_bf16 v[80:83], v[192:195], v[220:223], v[80:83]
	v_mfma_f32_16x16x32_bf16 v[68:71], v[184:187], v[228:231], v[68:71]
	v_mfma_f32_16x16x32_bf16 v[64:67], v[192:195], v[228:231], v[64:67]
	s_setprio 0
	s_barrier
	s_add_i32 s64, s56, s94
	v_lshl_add_u64 v[144:145], s[44:45], 0, v[132:133]
	s_mov_b32 m0, s64
	ds_read_b128 v[196:199], v159 offset:16384
	ds_read_b128 v[200:203], v159 offset:17408
	ds_read_b128 v[204:207], v159 offset:18432
	ds_read_b128 v[208:211], v159 offset:19456
	ds_read_b128 v[216:219], v159 offset:20480
	ds_read_b128 v[220:223], v159 offset:21504
	ds_read_b128 v[224:227], v159 offset:22528
	ds_read_b128 v[228:231], v159 offset:23552
	global_load_lds_dwordx4 v[144:145], off
	s_add_i32 m0, s64, 0x2000
	s_add_u32 s64, s44, 0x40000
	v_lshl_add_u64 v[148:149], s[44:45], 0, v[128:129]
	s_addc_u32 s65, s45, 0
	s_add_i32 s66, s57, s94
	global_load_lds_dwordx4 v[148:149], off
	v_lshl_add_u64 v[152:153], s[64:65], 0, v[132:133]
	s_mov_b32 m0, s66
	v_lshl_add_u64 v[156:157], s[46:47], 0, v[130:131]
	global_load_lds_dwordx4 v[152:153], off
	v_lshl_add_u64 v[152:153], s[64:65], 0, v[128:129]
	s_add_i32 m0, s66, 0x2000
	s_nop 0
	global_load_lds_dwordx4 v[152:153], off
	v_lshl_add_u64 v[152:153], s[46:47], 0, v[134:135]
	s_mov_b32 m0, s27
	s_nop 0
	global_load_lds_dwordx4 v[152:153], off
	s_mov_b32 m0, s41
	s_nop 0
	global_load_lds_dwordx4 v[156:157], off
	s_waitcnt vmcnt(8)
	s_waitcnt lgkmcnt(0)
	s_barrier
; #define PG8_STAGE(bufoff, gbase, voff) do { _Pragma("unroll") for (int _i = 0; _i < 2; ++_i) \
;         __builtin_amdgcn_global_load_lds((const unsigned*)((const char*)(gbase) + (voff)[_i]), (LAS unsigned*)(lds + (bufoff) + ldsw + _i * 8192), 16, 0, 0); } while (0)
; #define PG8_LDA(dst, b, h) do { _Pragma("unroll") for (int m = 0; m < 4; ++m) _Pragma("unroll") for (int k = 0; k < 2; ++k) dst[m][k] = *(const LAS bf16x8*)(lds + PG8_SA(b, h) + aoff + m * 2048 + k * 1024); } while (0)
; #define PG8_LDB(dst, b, h) do { _Pragma("unroll") for (int n = 0; n < 2; ++n) _Pragma("unroll") for (int k = 0; k < 2; ++k) dst[n][k] = *(const LAS bf16x8*)(lds + PG8_SB(b, h) + boff + n * 2048 + k * 1024); } while (0)
; #define PG8_MMA(ai, bj, At, Bt) do { __builtin_amdgcn_s_setprio(1); _Pragma("unroll") for (int m = 0; m < 4; ++m) _Pragma("unroll") for (int n = 0; n < 2; ++n) _Pragma("unroll") for (int k = 0; k < 2; ++k) \
;         acc[ai][bj][m][n] = __builtin_amdgcn_mfma_f32_16x16x32_bf16(Bt[n][k], At[m][k], acc[ai][bj][m][n], 0, 0, 0); __builtin_amdgcn_s_setprio(0); } while (0)
; #define PG8_WAIT_V(n) asm volatile("s_waitcnt vmcnt(" #n ")" ::: "memory")
; #define PG8_WAIT_L(n) asm volatile("s_waitcnt lgkmcnt(" #n ")" ::: "memory")
; #define PG8_BAR __builtin_amdgcn_s_barrier()
; #define PG8_SCHED __builtin_amdgcn_sched_barrier(0)
; template <class Epi>
; DI void gemm_phase(LAS unsigned char* lds, const int wid, const Gemm g, const Order& S, const Epi& E) {
;     ...
;             PG8_WAIT_V(8); PG8_WAIT_L(0); PG8_BAR; PG8_MMA(1, 0, At, B0); PG8_MMA(1, 1, At, B1); PG8_BAR; PG8_SCHED;
;             PG8_LDB(B0, 1, 0); PG8_LDB(B1, 1, 1); PG8_SCHED; PG8_LDA(At, 1, 0); PG8_STAGE(PG8_SA(0, 1), a2 + hstepA, voffA);
;             PG8_WAIT_V(8); PG8_WAIT_L(0); PG8_BAR; PG8_MMA(0, 0, At, B0); PG8_MMA(0, 1, At, B1); PG8_BAR; PG8_SCHED;
	s_setprio 1
	v_mfma_f32_16x16x32_bf16 v[60:63], v[164:167], v[196:199], 0
	v_mfma_f32_16x16x32_bf16 v[56:59], v[172:175], v[196:199], 0
	v_mfma_f32_16x16x32_bf16 v[44:47], v[164:167], v[204:207], 0
	v_mfma_f32_16x16x32_bf16 v[40:43], v[172:175], v[204:207], 0
	v_mfma_f32_16x16x32_bf16 v[28:31], v[164:167], v[216:219], 0
	v_mfma_f32_16x16x32_bf16 v[24:27], v[172:175], v[216:219], 0
	v_mfma_f32_16x16x32_bf16 v[12:15], v[164:167], v[224:227], 0
	v_mfma_f32_16x16x32_bf16 v[8:11], v[172:175], v[224:227], 0
	v_mfma_f32_16x16x32_bf16 v[60:63], v[168:171], v[200:203], v[60:63]
	v_mfma_f32_16x16x32_bf16 v[56:59], v[176:179], v[200:203], v[56:59]
	v_mfma_f32_16x16x32_bf16 v[44:47], v[168:171], v[208:211], v[44:47]
	v_mfma_f32_16x16x32_bf16 v[40:43], v[176:179], v[208:211], v[40:43]
	v_mfma_f32_16x16x32_bf16 v[28:31], v[168:171], v[220:223], v[28:31]
	v_mfma_f32_16x16x32_bf16 v[24:27], v[176:179], v[220:223], v[24:27]
	v_mfma_f32_16x16x32_bf16 v[12:15], v[168:171], v[228:231], v[12:15]
	v_mfma_f32_16x16x32_bf16 v[8:11], v[176:179], v[228:231], v[8:11]
	v_mfma_f32_16x16x32_bf16 v[52:55], v[180:183], v[196:199], 0
	v_mfma_f32_16x16x32_bf16 v[48:51], v[188:191], v[196:199], 0
	v_mfma_f32_16x16x32_bf16 v[36:39], v[180:183], v[204:207], 0
	v_mfma_f32_16x16x32_bf16 v[32:35], v[188:191], v[204:207], 0
	v_mfma_f32_16x16x32_bf16 v[20:23], v[180:183], v[216:219], 0
	v_mfma_f32_16x16x32_bf16 v[16:19], v[188:191], v[216:219], 0
	v_mfma_f32_16x16x32_bf16 v[4:7], v[180:183], v[224:227], 0
	v_mfma_f32_16x16x32_bf16 v[0:3], v[188:191], v[224:227], 0
	v_mfma_f32_16x16x32_bf16 v[52:55], v[184:187], v[200:203], v[52:55]
	v_mfma_f32_16x16x32_bf16 v[48:51], v[192:195], v[200:203], v[48:51]
	v_mfma_f32_16x16x32_bf16 v[36:39], v[184:187], v[208:211], v[36:39]
	v_mfma_f32_16x16x32_bf16 v[32:35], v[192:195], v[208:211], v[32:35]
	v_mfma_f32_16x16x32_bf16 v[20:23], v[184:187], v[220:223], v[20:23]
	v_mfma_f32_16x16x32_bf16 v[16:19], v[192:195], v[220:223], v[16:19]
	v_mfma_f32_16x16x32_bf16 v[4:7], v[184:187], v[228:231], v[4:7]
	v_mfma_f32_16x16x32_bf16 v[0:3], v[192:195], v[228:231], v[0:3]
	s_setprio 0
	s_barrier
	s_add_i32 s64, 0, 0x18000
	v_add_u32_e32 v146, s64, v147
	s_add_i32 s65, 0, 0x1c000
	ds_read_b128 v[164:167], v146
	ds_read_b128 v[168:171], v146 offset:1024
	ds_read_b128 v[172:175], v146 offset:2048
	ds_read_b128 v[176:179], v146 offset:3072
	v_add_u32_e32 v146, s65, v147
	ds_read_b128 v[180:183], v146
	ds_read_b128 v[184:187], v146 offset:1024
	ds_read_b128 v[188:191], v146 offset:2048
	ds_read_b128 v[192:195], v146 offset:3072
	s_add_u32 s46, s46, 0x40000
	s_addc_u32 s47, s47, 0
	s_mov_b32 m0, s48
	v_lshl_add_u64 v[160:161], s[46:47], 0, v[134:135]
	ds_read_b128 v[196:199], v159 offset:32768
	ds_read_b128 v[200:203], v159 offset:33792
	ds_read_b128 v[204:207], v159 offset:34816
	ds_read_b128 v[208:211], v159 offset:35840
	ds_read_b128 v[216:219], v159 offset:36864
	ds_read_b128 v[220:223], v159 offset:37888
	ds_read_b128 v[224:227], v159 offset:38912
	ds_read_b128 v[228:231], v159 offset:39936
	global_load_lds_dwordx4 v[160:161], off
	v_lshl_add_u64 v[160:161], s[46:47], 0, v[130:131]
	s_mov_b32 m0, s49
	s_nop 0
	global_load_lds_dwordx4 v[160:161], off
	s_waitcnt vmcnt(8)
	s_waitcnt lgkmcnt(0)
	s_barrier
	s_setprio 1
	v_mfma_f32_16x16x32_bf16 v[124:127], v[164:167], v[196:199], v[124:127]
	v_mfma_f32_16x16x32_bf16 v[120:123], v[172:175], v[196:199], v[120:123]
	v_mfma_f32_16x16x32_bf16 v[108:111], v[164:167], v[204:207], v[108:111]
	v_mfma_f32_16x16x32_bf16 v[104:107], v[172:175], v[204:207], v[104:107]
	v_mfma_f32_16x16x32_bf16 v[92:95], v[164:167], v[216:219], v[92:95]
	v_mfma_f32_16x16x32_bf16 v[88:91], v[172:175], v[216:219], v[88:91]
	v_mfma_f32_16x16x32_bf16 v[76:79], v[164:167], v[224:227], v[76:79]
	v_mfma_f32_16x16x32_bf16 v[72:75], v[172:175], v[224:227], v[72:75]
	v_mfma_f32_16x16x32_bf16 v[124:127], v[168:171], v[200:203], v[124:127]
	v_mfma_f32_16x16x32_bf16 v[120:123], v[176:179], v[200:203], v[120:123]
	v_mfma_f32_16x16x32_bf16 v[108:111], v[168:171], v[208:211], v[108:111]
	v_mfma_f32_16x16x32_bf16 v[104:107], v[176:179], v[208:211], v[104:107]
	v_mfma_f32_16x16x32_bf16 v[92:95], v[168:171], v[220:223], v[92:95]
	v_mfma_f32_16x16x32_bf16 v[88:91], v[176:179], v[220:223], v[88:91]
	v_mfma_f32_16x16x32_bf16 v[76:79], v[168:171], v[228:231], v[76:79]
	v_mfma_f32_16x16x32_bf16 v[72:75], v[176:179], v[228:231], v[72:75]
	v_mfma_f32_16x16x32_bf16 v[116:119], v[180:183], v[196:199], v[116:119]
	v_mfma_f32_16x16x32_bf16 v[112:115], v[188:191], v[196:199], v[112:115]
	v_mfma_f32_16x16x32_bf16 v[100:103], v[180:183], v[204:207], v[100:103]
	v_mfma_f32_16x16x32_bf16 v[96:99], v[188:191], v[204:207], v[96:99]
	v_mfma_f32_16x16x32_bf16 v[84:87], v[180:183], v[216:219], v[84:87]
	v_mfma_f32_16x16x32_bf16 v[80:83], v[188:191], v[216:219], v[80:83]
	v_mfma_f32_16x16x32_bf16 v[68:71], v[180:183], v[224:227], v[68:71]
	v_mfma_f32_16x16x32_bf16 v[64:67], v[188:191], v[224:227], v[64:67]
	v_mfma_f32_16x16x32_bf16 v[116:119], v[184:187], v[200:203], v[116:119]
	v_mfma_f32_16x16x32_bf16 v[112:115], v[192:195], v[200:203], v[112:115]
	v_mfma_f32_16x16x32_bf16 v[100:103], v[184:187], v[208:211], v[100:103]
	v_mfma_f32_16x16x32_bf16 v[96:99], v[192:195], v[208:211], v[96:99]
	v_mfma_f32_16x16x32_bf16 v[84:87], v[184:187], v[220:223], v[84:87]
	v_mfma_f32_16x16x32_bf16 v[80:83], v[192:195], v[220:223], v[80:83]
	v_mfma_f32_16x16x32_bf16 v[68:71], v[184:187], v[228:231], v[68:71]
	v_mfma_f32_16x16x32_bf16 v[64:67], v[192:195], v[228:231], v[64:67]
	s_setprio 0
	s_barrier
; #define PG8_STAGE(bufoff, gbase, voff) do { _Pragma("unroll") for (int _i = 0; _i < 2; ++_i) \
;         __builtin_amdgcn_global_load_lds((const unsigned*)((const char*)(gbase) + (voff)[_i]), (LAS unsigned*)(lds + (bufoff) + ldsw + _i * 8192), 16, 0, 0); } while (0)
; #define PG8_LDA(dst, b, h) do { _Pragma("unroll") for (int m = 0; m < 4; ++m) _Pragma("unroll") for (int k = 0; k < 2; ++k) dst[m][k] = *(const LAS bf16x8*)(lds + PG8_SA(b, h) + aoff + m * 2048 + k * 1024); } while (0)
; #define PG8_MMA(ai, bj, At, Bt) do { __builtin_amdgcn_s_setprio(1); _Pragma("unroll") for (int m = 0; m < 4; ++m) _Pragma("unroll") for (int n = 0; n < 2; ++n) _Pragma("unroll") for (int k = 0; k < 2; ++k) \
;         acc[ai][bj][m][n] = __builtin_amdgcn_mfma_f32_16x16x32_bf16(Bt[n][k], At[m][k], acc[ai][bj][m][n], 0, 0, 0); __builtin_amdgcn_s_setprio(0); } while (0)
; #define PG8_WAIT_V(n) asm volatile("s_waitcnt vmcnt(" #n ")" ::: "memory")
; #define PG8_WAIT_L(n) asm volatile("s_waitcnt lgkmcnt(" #n ")" ::: "memory")
; #define PG8_BAR __builtin_amdgcn_s_barrier()
; #define PG8_SCHED __builtin_amdgcn_sched_barrier(0)
; template <class Epi>
; DI void gemm_phase(LAS unsigned char* lds, const int wid, const Gemm g, const Order& S, const Epi& E) {
;     ...
;             PG8_LDA(At, 1, 1); PG8_STAGE(PG8_SB(1, 0), b3, voffB); PG8_STAGE(PG8_SB(1, 1), b3 + hstepB, voffB); PG8_STAGE(PG8_SA(1, 0), a3, voffA);
;             PG8_WAIT_V(8); PG8_WAIT_L(0); PG8_BAR; PG8_MMA(1, 0, At, B0); PG8_MMA(1, 1, At, B1); PG8_BAR; PG8_SCHED;
;         }
	s_add_i32 s46, s64, s94
	v_lshl_add_u64 v[144:145], v[144:145], 0, s[16:17]
	s_mov_b32 m0, s46
	ds_read_b128 v[196:199], v159 offset:49152
	ds_read_b128 v[200:203], v159 offset:50176
	ds_read_b128 v[204:207], v159 offset:51200
	ds_read_b128 v[208:211], v159 offset:52224
	ds_read_b128 v[216:219], v159 offset:53248
	ds_read_b128 v[220:223], v159 offset:54272
	ds_read_b128 v[224:227], v159 offset:55296
	ds_read_b128 v[228:231], v159 offset:56320
	global_load_lds_dwordx4 v[144:145], off
	s_add_i32 m0, s46, 0x2000
	s_add_u32 s44, s44, 0x40080
	v_lshl_add_u64 v[144:145], v[148:149], 0, s[16:17]
	s_addc_u32 s45, s45, 0
	s_add_i32 s46, s65, s94
	global_load_lds_dwordx4 v[144:145], off
	v_lshl_add_u64 v[144:145], s[44:45], 0, v[132:133]
	s_mov_b32 m0, s46
	s_nop 0
	global_load_lds_dwordx4 v[144:145], off
	v_lshl_add_u64 v[144:145], s[44:45], 0, v[128:129]
	s_add_i32 m0, s46, 0x2000
	s_nop 0
	global_load_lds_dwordx4 v[144:145], off
	v_lshl_add_u64 v[144:145], v[152:153], 0, s[16:17]
	s_mov_b32 m0, s51
	s_nop 0
	global_load_lds_dwordx4 v[144:145], off
	v_lshl_add_u64 v[144:145], v[156:157], 0, s[16:17]
	s_mov_b32 m0, s52
	s_nop 0
	global_load_lds_dwordx4 v[144:145], off
	s_waitcnt vmcnt(8)
	s_waitcnt lgkmcnt(0)
	s_barrier
	s_setprio 1
	v_mfma_f32_16x16x32_bf16 v[60:63], v[164:167], v[196:199], v[60:63]
	v_mfma_f32_16x16x32_bf16 v[56:59], v[172:175], v[196:199], v[56:59]
	v_mfma_f32_16x16x32_bf16 v[44:47], v[164:167], v[204:207], v[44:47]
	v_mfma_f32_16x16x32_bf16 v[40:43], v[172:175], v[204:207], v[40:43]
	v_mfma_f32_16x16x32_bf16 v[28:31], v[164:167], v[216:219], v[28:31]
	v_mfma_f32_16x16x32_bf16 v[24:27], v[172:175], v[216:219], v[24:27]
	v_mfma_f32_16x16x32_bf16 v[12:15], v[164:167], v[224:227], v[12:15]
	v_mfma_f32_16x16x32_bf16 v[8:11], v[172:175], v[224:227], v[8:11]
	v_mfma_f32_16x16x32_bf16 v[60:63], v[168:171], v[200:203], v[60:63]
	v_mfma_f32_16x16x32_bf16 v[56:59], v[176:179], v[200:203], v[56:59]
	v_mfma_f32_16x16x32_bf16 v[44:47], v[168:171], v[208:211], v[44:47]
	v_mfma_f32_16x16x32_bf16 v[40:43], v[176:179], v[208:211], v[40:43]
	v_mfma_f32_16x16x32_bf16 v[28:31], v[168:171], v[220:223], v[28:31]
	v_mfma_f32_16x16x32_bf16 v[24:27], v[176:179], v[220:223], v[24:27]
	v_mfma_f32_16x16x32_bf16 v[12:15], v[168:171], v[228:231], v[12:15]
	v_mfma_f32_16x16x32_bf16 v[8:11], v[176:179], v[228:231], v[8:11]
	v_mfma_f32_16x16x32_bf16 v[52:55], v[180:183], v[196:199], v[52:55]
	v_mfma_f32_16x16x32_bf16 v[48:51], v[188:191], v[196:199], v[48:51]
	v_mfma_f32_16x16x32_bf16 v[36:39], v[180:183], v[204:207], v[36:39]
	v_mfma_f32_16x16x32_bf16 v[32:35], v[188:191], v[204:207], v[32:35]
	v_mfma_f32_16x16x32_bf16 v[20:23], v[180:183], v[216:219], v[20:23]
	v_mfma_f32_16x16x32_bf16 v[16:19], v[188:191], v[216:219], v[16:19]
	v_mfma_f32_16x16x32_bf16 v[4:7], v[180:183], v[224:227], v[4:7]
	v_mfma_f32_16x16x32_bf16 v[0:3], v[188:191], v[224:227], v[0:3]
	v_mfma_f32_16x16x32_bf16 v[52:55], v[184:187], v[200:203], v[52:55]
	v_mfma_f32_16x16x32_bf16 v[48:51], v[192:195], v[200:203], v[48:51]
	v_mfma_f32_16x16x32_bf16 v[36:39], v[184:187], v[208:211], v[36:39]
	v_mfma_f32_16x16x32_bf16 v[32:35], v[192:195], v[208:211], v[32:35]
	v_mfma_f32_16x16x32_bf16 v[20:23], v[184:187], v[220:223], v[20:23]
	v_mfma_f32_16x16x32_bf16 v[16:19], v[192:195], v[220:223], v[16:19]
	v_mfma_f32_16x16x32_bf16 v[4:7], v[184:187], v[228:231], v[4:7]
	v_mfma_f32_16x16x32_bf16 v[0:3], v[192:195], v[228:231], v[0:3]
	s_setprio 0
	s_barrier
	s_add_i32 s63, s63, 2
	s_add_u32 s42, s42, 0x100
	s_addc_u32 s43, s43, 0
	s_add_u32 s61, s61, 0x100
	s_addc_u32 s62, s62, 0
	s_cmp_gt_u32 s63, 13
	s_cbranch_scc0 .LBB0_228
	s_branch .Lpeel_exit_0

; DI float silu(float x) { return x * sigm(x); }
; DI u32x4 pack8(f32x4 a, f32x4 b) { u32x4 w; w.x = pk2(a[0], a[1]); w.y = pk2(a[2], a[3]); w.z = pk2(b[0], b[1]); w.w = pk2(b[2], b[3]); return w; }
; #define EPI_ROWS(ai, m) _Pragma("unroll") for (int ai = 0; ai < 2; ++ai) _Pragma("unroll") for (int m = 0; m < 4; ++m)
; #define EPI_RSTD8(rr, ssqp, invn) float rr[2][4]; EPI_ROWS(ai, m) rr[ai][m] = (ssqp)[epi_row(u, ai, wr, m, fr)]; EPI_FENCE(); EPI_ROWS(ai, m) rr[ai][m] = rstd_of(rr[ai][m], invn);
; DI float rstd_of(float ssq, float invn) { return __builtin_amdgcn_rsqf(ssq * invn + EPS); }
;     DI void operator()(const Acc& acc, const Unit& u, int wr, int wc, int fr, int fq) const {
;         const int cb = u.pn * 128 + wc * 32 + 8 * fq;
;         EPI_RSTD8(rr, ssq, 1.0f / D)
;         EPI_ROWS(ai, m) { const int row = epi_row(u, ai, wr, m, fr); const float r = rr[ai][m];
;             f32x4 v[2];
; #pragma unroll
;             for (int n = 0; n < 2; ++n)
; #pragma unroll
;                 for (int j = 0; j < 4; ++j) v[n][j] = silu(acc[ai][0][m][n][j] * r) * (acc[ai][1][m][n][j] * r);
;             *(u32x4*)(act + (size_t)row * FF + cb) = pack8(v[0], v[1]); }
.LBB0_231:
	s_lshl_b32 s31, s40, 8
	s_add_i32 s31, s31, s95
	v_mbcnt_lo_u32_b32 v146, -1, 0
	v_mbcnt_hi_u32_b32 v146, -1, v146
	s_andn2_b64 vcc, exec, s[6:7]
	v_and_or_b32 v170, v146, 15, s31
	v_ashrrev_i32_e32 v171, 31, v170
	v_or_b32_e32 v168, 16, v170
	v_ashrrev_i32_e32 v169, 31, v168
	v_or_b32_e32 v164, 32, v170
	v_or_b32_e32 v160, 48, v170
	v_add_u32_e32 v156, 0x80, v170
	v_add_u32_e32 v152, 0x90, v170
	v_add_u32_e32 v148, 0xa0, v170
	v_add_u32_e32 v144, 0xb0, v170
	v_ashrrev_i32_e32 v165, 31, v164
	v_ashrrev_i32_e32 v161, 31, v160
	v_ashrrev_i32_e32 v157, 31, v156
	v_ashrrev_i32_e32 v153, 31, v152
	v_ashrrev_i32_e32 v149, 31, v148
	v_ashrrev_i32_e32 v145, 31, v144
	s_lshl_b32 s31, s58, 7
	v_ashrrev_i32_e32 v146, 1, v146
	s_or_b32 s31, s31, s22
	v_and_b32_e32 v146, -8, v146
	v_add_u32_e32 v172, s31, v146
	v_ashrrev_i32_e32 v173, 31, v172
	s_mov_b64 s[6:7], -1
	s_waitcnt vmcnt(8)
	v_fmamk_f32 v146, v236, 0x3a800000, v163
	v_rsq_f32_e32 v174, v146
	v_fmamk_f32 v145, v237, 0x3a800000, v163
	v_fmamk_f32 v146, v238, 0x3a800000, v163
	v_fmamk_f32 v149, v239, 0x3a800000, v163
	v_fmamk_f32 v150, v240, 0x3a800000, v163
	v_fmamk_f32 v153, v241, 0x3a800000, v163
	v_fmamk_f32 v157, v242, 0x3a800000, v163
	v_fmamk_f32 v161, v243, 0x3a800000, v163
	v_mul_f32_e32 v236, 0x3f317218, v174
	v_mul_f32_e32 v174, 0x3fb8aa3b, v174
	v_pk_mul_f32 v[124:125], v[124:125], v[174:175] op_sel_hi:[1,0]
	v_pk_mul_f32 v[126:127], v[126:127], v[174:175] op_sel_hi:[1,0]
	v_pk_mul_f32 v[120:121], v[120:121], v[174:175] op_sel_hi:[1,0]
	v_rsq_f32_e32 v176, v145
	v_rsq_f32_e32 v166, v146
	v_rsq_f32_e32 v162, v149
	v_rsq_f32_e32 v158, v150
	v_rsq_f32_e32 v154, v153
	v_rsq_f32_e32 v150, v157
	v_rsq_f32_e32 v146, v161
	s_nop 0
	v_mul_f32_e32 v238, 0x3f317218, v176
	v_mul_f32_e32 v240, 0x3f317218, v166
	v_mul_f32_e32 v242, 0x3f317218, v162
	v_mul_f32_e32 v244, 0x3f317218, v158
	v_mul_f32_e32 v246, 0x3f317218, v154
	v_mul_f32_e32 v248, 0x3f317218, v150
	v_mul_f32_e32 v250, 0x3f317218, v146
	v_mul_f32_e32 v176, 0x3fb8aa3b, v176
	v_mul_f32_e32 v166, 0x3fb8aa3b, v166
	v_mul_f32_e32 v162, 0x3fb8aa3b, v162
	v_mul_f32_e32 v158, 0x3fb8aa3b, v158
	v_mul_f32_e32 v154, 0x3fb8aa3b, v154
	v_mul_f32_e32 v150, 0x3fb8aa3b, v150
	v_mul_f32_e32 v146, 0x3fb8aa3b, v146
	v_pk_mul_f32 v[122:123], v[122:123], v[174:175] op_sel_hi:[1,0]
	v_exp_f32_e64 v145, -v124
	v_exp_f32_e64 v149, -v125
	v_exp_f32_e64 v153, -v126
	v_exp_f32_e64 v157, -v127
	v_exp_f32_e64 v161, -v120
	v_exp_f32_e64 v165, -v121
	v_exp_f32_e64 v167, -v122
	v_exp_f32_e64 v169, -v123
	v_add_f32_e32 v145, 1.0, v145
	v_add_f32_e32 v149, 1.0, v149
	v_add_f32_e32 v153, 1.0, v153
	v_add_f32_e32 v157, 1.0, v157
	v_add_f32_e32 v161, 1.0, v161
	v_add_f32_e32 v165, 1.0, v165
	v_add_f32_e32 v167, 1.0, v167
	v_add_f32_e32 v169, 1.0, v169
	v_rcp_f32_e32 v178, v145
	v_rcp_f32_e32 v179, v149
	v_rcp_f32_e32 v180, v153
	v_rcp_f32_e32 v181, v157
	v_rcp_f32_e32 v182, v161
	v_rcp_f32_e32 v183, v165
	v_rcp_f32_e32 v184, v167
	v_rcp_f32_e32 v185, v169
	v_pk_mul_f32 v[116:117], v[116:117], v[236:237] op_sel_hi:[1,0]
	v_pk_mul_f32 v[118:119], v[118:119], v[236:237] op_sel_hi:[1,0]
	v_pk_mul_f32 v[112:113], v[112:113], v[236:237] op_sel_hi:[1,0]
	v_pk_mul_f32 v[124:125], v[124:125], v[178:179]
	v_pk_mul_f32 v[126:127], v[126:127], v[180:181]
	v_pk_mul_f32 v[120:121], v[120:121], v[182:183]
	v_pk_mul_f32 v[116:117], v[116:117], v[124:125]
	v_pk_mul_f32 v[118:119], v[118:119], v[126:127]
	v_pk_mul_f32 v[112:113], v[112:113], v[120:121]
	v_pk_mul_f32 v[120:121], v[122:123], v[184:185]
	v_pk_mul_f32 v[114:115], v[114:115], v[236:237] op_sel_hi:[1,0]
	v_cvt_pk_bf16_f32 v116, v116, v117
	v_pk_mul_f32 v[114:115], v[114:115], v[120:121]
	v_cvt_pk_bf16_f32 v117, v118, v119
	v_cvt_pk_bf16_f32 v118, v112, v113
	v_mov_b64_e32 v[112:113], s[14:15]
	v_cvt_pk_bf16_f32 v119, v114, v115
	v_mad_i64_i32 v[120:121], s[42:43], v170, s55, v[112:113]
	v_lshlrev_b64 v[114:115], 1, v[172:173]
	v_pk_mul_f32 v[108:109], v[108:109], v[176:177] op_sel_hi:[1,0]
	v_lshl_add_u64 v[120:121], v[120:121], 0, v[114:115]
	v_pk_mul_f32 v[110:111], v[110:111], v[176:177] op_sel_hi:[1,0]
	v_exp_f32_e64 v122, -v108
	v_exp_f32_e64 v123, -v109
	global_store_dwordx4 v[120:121], v[116:119], off
	v_pk_mul_f32 v[100:101], v[100:101], v[238:239] op_sel_hi:[1,0]
	v_pk_mul_f32 v[104:105], v[104:105], v[176:177] op_sel_hi:[1,0]
	v_exp_f32_e64 v118, -v110
	v_exp_f32_e64 v119, -v111
	v_add_f32_e32 v116, 1.0, v122
	v_add_f32_e32 v117, 1.0, v123
	v_rcp_f32_e32 v116, v116
	v_rcp_f32_e32 v117, v117
	v_add_f32_e32 v118, 1.0, v118
	v_add_f32_e32 v119, 1.0, v119
	v_rcp_f32_e32 v118, v118
	v_rcp_f32_e32 v119, v119
	v_pk_mul_f32 v[108:109], v[108:109], v[116:117]
	v_pk_mul_f32 v[102:103], v[102:103], v[238:239] op_sel_hi:[1,0]
	v_pk_mul_f32 v[100:101], v[100:101], v[108:109]
	v_pk_mul_f32 v[108:109], v[110:111], v[118:119]
	v_exp_f32_e64 v110, -v104
	v_exp_f32_e64 v111, -v105
	v_pk_mul_f32 v[106:107], v[106:107], v[176:177] op_sel_hi:[1,0]
	v_pk_mul_f32 v[102:103], v[102:103], v[108:109]
	v_add_f32_e32 v108, 1.0, v110
	v_add_f32_e32 v109, 1.0, v111
	v_exp_f32_e64 v110, -v106
	v_exp_f32_e64 v111, -v107
	v_rcp_f32_e32 v108, v108
	v_rcp_f32_e32 v109, v109
	v_add_f32_e32 v110, 1.0, v110
	v_add_f32_e32 v111, 1.0, v111
	v_rcp_f32_e32 v110, v110
	v_rcp_f32_e32 v111, v111
	v_pk_mul_f32 v[104:105], v[104:105], v[108:109]
	v_pk_mul_f32 v[96:97], v[96:97], v[238:239] op_sel_hi:[1,0]
	v_pk_mul_f32 v[98:99], v[98:99], v[238:239] op_sel_hi:[1,0]
	v_pk_mul_f32 v[104:105], v[96:97], v[104:105]
	v_pk_mul_f32 v[96:97], v[106:107], v[110:111]
	v_pk_mul_f32 v[92:93], v[92:93], v[166:167] op_sel_hi:[1,0]
	v_pk_mul_f32 v[106:107], v[98:99], v[96:97]
; DI float silu(float x) { return x * sigm(x); }
; DI u32x4 pack8(f32x4 a, f32x4 b) { u32x4 w; w.x = pk2(a[0], a[1]); w.y = pk2(a[2], a[3]); w.z = pk2(b[0], b[1]); w.w = pk2(b[2], b[3]); return w; }
; #define EPI_ROWS(ai, m) _Pragma("unroll") for (int ai = 0; ai < 2; ++ai) _Pragma("unroll") for (int m = 0; m < 4; ++m)
;     DI void operator()(const Acc& acc, const Unit& u, int wr, int wc, int fr, int fq) const {
;     ...
;         EPI_ROWS(ai, m) { const int row = epi_row(u, ai, wr, m, fr); const float r = rr[ai][m];
;             f32x4 v[2];
; #pragma unroll
;             for (int n = 0; n < 2; ++n)
; #pragma unroll
;                 for (int j = 0; j < 4; ++j) v[n][j] = silu(acc[ai][0][m][n][j] * r) * (acc[ai][1][m][n][j] * r);
;             *(u32x4*)(act + (size_t)row * FF + cb) = pack8(v[0], v[1]); }
	v_cvt_pk_bf16_f32 v96, v100, v101
	v_mad_i64_i32 v[100:101], s[42:43], v168, s55, v[112:113]
	v_cvt_pk_bf16_f32 v97, v102, v103
	v_cvt_pk_bf16_f32 v98, v104, v105
	v_cvt_pk_bf16_f32 v99, v106, v107
	v_lshl_add_u64 v[100:101], v[100:101], 0, v[114:115]
	v_pk_mul_f32 v[94:95], v[94:95], v[166:167] op_sel_hi:[1,0]
	v_exp_f32_e64 v102, -v92
	v_exp_f32_e64 v103, -v93
	global_store_dwordx4 v[100:101], v[96:99], off
	v_pk_mul_f32 v[84:85], v[84:85], v[240:241] op_sel_hi:[1,0]
	v_pk_mul_f32 v[88:89], v[88:89], v[166:167] op_sel_hi:[1,0]
	v_exp_f32_e64 v98, -v94
	v_exp_f32_e64 v99, -v95
	v_add_f32_e32 v96, 1.0, v102
	v_add_f32_e32 v97, 1.0, v103
	v_rcp_f32_e32 v96, v96
	v_rcp_f32_e32 v97, v97
	v_add_f32_e32 v98, 1.0, v98
	v_add_f32_e32 v99, 1.0, v99
	v_rcp_f32_e32 v98, v98
	v_rcp_f32_e32 v99, v99
	v_pk_mul_f32 v[92:93], v[92:93], v[96:97]
	v_pk_mul_f32 v[86:87], v[86:87], v[240:241] op_sel_hi:[1,0]
	v_pk_mul_f32 v[84:85], v[84:85], v[92:93]
	v_pk_mul_f32 v[92:93], v[94:95], v[98:99]
	v_exp_f32_e64 v94, -v88
	v_exp_f32_e64 v95, -v89
	v_pk_mul_f32 v[90:91], v[90:91], v[166:167] op_sel_hi:[1,0]
	v_pk_mul_f32 v[86:87], v[86:87], v[92:93]
	v_add_f32_e32 v92, 1.0, v94
	v_add_f32_e32 v93, 1.0, v95
	v_exp_f32_e64 v94, -v90
	v_exp_f32_e64 v95, -v91
	v_rcp_f32_e32 v92, v92
	v_rcp_f32_e32 v93, v93
	v_add_f32_e32 v94, 1.0, v94
	v_add_f32_e32 v95, 1.0, v95
	v_rcp_f32_e32 v94, v94
	v_rcp_f32_e32 v95, v95
	v_pk_mul_f32 v[88:89], v[88:89], v[92:93]
	v_pk_mul_f32 v[80:81], v[80:81], v[240:241] op_sel_hi:[1,0]
	v_pk_mul_f32 v[82:83], v[82:83], v[240:241] op_sel_hi:[1,0]
	v_pk_mul_f32 v[88:89], v[80:81], v[88:89]
	v_pk_mul_f32 v[80:81], v[90:91], v[94:95]
	v_pk_mul_f32 v[76:77], v[76:77], v[162:163] op_sel_hi:[1,0]
	v_pk_mul_f32 v[90:91], v[82:83], v[80:81]
	v_cvt_pk_bf16_f32 v80, v84, v85
	v_mad_i64_i32 v[84:85], s[42:43], v164, s55, v[112:113]
	v_cvt_pk_bf16_f32 v81, v86, v87
	v_cvt_pk_bf16_f32 v82, v88, v89
	v_cvt_pk_bf16_f32 v83, v90, v91
	v_lshl_add_u64 v[84:85], v[84:85], 0, v[114:115]
	v_pk_mul_f32 v[78:79], v[78:79], v[162:163] op_sel_hi:[1,0]
	v_exp_f32_e64 v86, -v76
	v_exp_f32_e64 v87, -v77
	global_store_dwordx4 v[84:85], v[80:83], off
	v_pk_mul_f32 v[68:69], v[68:69], v[242:243] op_sel_hi:[1,0]
	v_pk_mul_f32 v[72:73], v[72:73], v[162:163] op_sel_hi:[1,0]
	v_exp_f32_e64 v82, -v78
	v_exp_f32_e64 v83, -v79
	v_add_f32_e32 v80, 1.0, v86
	v_add_f32_e32 v81, 1.0, v87
	v_rcp_f32_e32 v80, v80
	v_rcp_f32_e32 v81, v81
	v_add_f32_e32 v82, 1.0, v82
	v_add_f32_e32 v83, 1.0, v83
	v_rcp_f32_e32 v82, v82
	v_rcp_f32_e32 v83, v83
	v_pk_mul_f32 v[76:77], v[76:77], v[80:81]
	v_pk_mul_f32 v[70:71], v[70:71], v[242:243] op_sel_hi:[1,0]
	v_pk_mul_f32 v[68:69], v[68:69], v[76:77]
	v_pk_mul_f32 v[76:77], v[78:79], v[82:83]
	v_exp_f32_e64 v78, -v72
	v_exp_f32_e64 v79, -v73
	v_pk_mul_f32 v[74:75], v[74:75], v[162:163] op_sel_hi:[1,0]
	v_pk_mul_f32 v[70:71], v[70:71], v[76:77]
	v_add_f32_e32 v76, 1.0, v78
	v_add_f32_e32 v77, 1.0, v79
	v_exp_f32_e64 v78, -v74
	v_exp_f32_e64 v79, -v75
	v_rcp_f32_e32 v76, v76
	v_rcp_f32_e32 v77, v77
	v_add_f32_e32 v78, 1.0, v78
	v_add_f32_e32 v79, 1.0, v79
	v_rcp_f32_e32 v78, v78
	v_rcp_f32_e32 v79, v79
	v_pk_mul_f32 v[72:73], v[72:73], v[76:77]
	v_pk_mul_f32 v[64:65], v[64:65], v[242:243] op_sel_hi:[1,0]
	v_pk_mul_f32 v[66:67], v[66:67], v[242:243] op_sel_hi:[1,0]
	v_pk_mul_f32 v[72:73], v[64:65], v[72:73]
	v_pk_mul_f32 v[64:65], v[74:75], v[78:79]
	v_pk_mul_f32 v[60:61], v[60:61], v[158:159] op_sel_hi:[1,0]
	v_pk_mul_f32 v[74:75], v[66:67], v[64:65]
	v_cvt_pk_bf16_f32 v64, v68, v69
	v_mad_i64_i32 v[68:69], s[42:43], v160, s55, v[112:113]
	v_cvt_pk_bf16_f32 v65, v70, v71
	v_cvt_pk_bf16_f32 v66, v72, v73
	v_cvt_pk_bf16_f32 v67, v74, v75
	v_lshl_add_u64 v[68:69], v[68:69], 0, v[114:115]
	v_pk_mul_f32 v[62:63], v[62:63], v[158:159] op_sel_hi:[1,0]
	v_exp_f32_e64 v70, -v60
	v_exp_f32_e64 v71, -v61
	global_store_dwordx4 v[68:69], v[64:67], off
	v_pk_mul_f32 v[52:53], v[52:53], v[244:245] op_sel_hi:[1,0]
	v_pk_mul_f32 v[56:57], v[56:57], v[158:159] op_sel_hi:[1,0]
	v_exp_f32_e64 v66, -v62
	v_exp_f32_e64 v67, -v63
	v_add_f32_e32 v64, 1.0, v70
	v_add_f32_e32 v65, 1.0, v71
	v_rcp_f32_e32 v64, v64
	v_rcp_f32_e32 v65, v65
	v_add_f32_e32 v66, 1.0, v66
	v_add_f32_e32 v67, 1.0, v67
	v_rcp_f32_e32 v66, v66
	v_rcp_f32_e32 v67, v67
	v_pk_mul_f32 v[60:61], v[60:61], v[64:65]
	v_pk_mul_f32 v[54:55], v[54:55], v[244:245] op_sel_hi:[1,0]
	v_pk_mul_f32 v[52:53], v[52:53], v[60:61]
	v_pk_mul_f32 v[60:61], v[62:63], v[66:67]
	v_exp_f32_e64 v62, -v56
	v_exp_f32_e64 v63, -v57
	v_pk_mul_f32 v[58:59], v[58:59], v[158:159] op_sel_hi:[1,0]
	v_pk_mul_f32 v[54:55], v[54:55], v[60:61]
	v_add_f32_e32 v60, 1.0, v62
	v_add_f32_e32 v61, 1.0, v63
	v_exp_f32_e64 v62, -v58
	v_exp_f32_e64 v63, -v59
	v_rcp_f32_e32 v60, v60
	v_rcp_f32_e32 v61, v61
	v_add_f32_e32 v62, 1.0, v62
	v_add_f32_e32 v63, 1.0, v63
	v_rcp_f32_e32 v62, v62
	v_rcp_f32_e32 v63, v63
	v_pk_mul_f32 v[56:57], v[56:57], v[60:61]
	v_pk_mul_f32 v[48:49], v[48:49], v[244:245] op_sel_hi:[1,0]
	v_pk_mul_f32 v[50:51], v[50:51], v[244:245] op_sel_hi:[1,0]
	v_pk_mul_f32 v[56:57], v[48:49], v[56:57]
	v_pk_mul_f32 v[48:49], v[58:59], v[62:63]
	v_pk_mul_f32 v[44:45], v[44:45], v[154:155] op_sel_hi:[1,0]
	v_pk_mul_f32 v[58:59], v[50:51], v[48:49]
	v_cvt_pk_bf16_f32 v48, v52, v53
	v_mad_i64_i32 v[52:53], s[42:43], v156, s55, v[112:113]
	v_cvt_pk_bf16_f32 v49, v54, v55
; DI float silu(float x) { return x * sigm(x); }
; DI int lane_id() { int l; asm volatile("v_mbcnt_lo_u32_b32 %0, -1, 0\n\tv_mbcnt_hi_u32_b32 %0, -1, %0" : "=v"(l)); return l; }
; DI u32x4 pack8(f32x4 a, f32x4 b) { u32x4 w; w.x = pk2(a[0], a[1]); w.y = pk2(a[2], a[3]); w.z = pk2(b[0], b[1]); w.w = pk2(b[2], b[3]); return w; }
; #define PG8_BAR __builtin_amdgcn_s_barrier()
; #define EPI_ROWS(ai, m) _Pragma("unroll") for (int ai = 0; ai < 2; ++ai) _Pragma("unroll") for (int m = 0; m < 4; ++m)
; template <class Epi>
; DI void gemm_phase(LAS unsigned char* lds, const int wid, const Gemm g, const Order& S, const Epi& E) {
;     ...
;         if (wr == 0) PG8_BAR;
;         { const int le = lane_id(); E(acc, cur, wr, wc, le & 15, le >> 4); }
;         if (!has_next) break;
; #pragma unroll
;         for (int a = 0; a < 2; ++a)
; #pragma unroll
;             for (int b = 0; b < 2; ++b)
; #pragma unroll
;                 for (int m = 0; m < 4; ++m)
; #pragma unroll
;                     for (int n = 0; n < 2; ++n) acc[a][b][m][n] = (f32x4){0.f, 0.f, 0.f, 0.f};
;         cur = nxt; cA = nA; cB = nB; ++ui;
;         if (wr == 1) PG8_BAR;
;     DI void operator()(const Acc& acc, const Unit& u, int wr, int wc, int fr, int fq) const {
;     ...
;         EPI_ROWS(ai, m) { const int row = epi_row(u, ai, wr, m, fr); const float r = rr[ai][m];
;             f32x4 v[2];
; #pragma unroll
;             for (int n = 0; n < 2; ++n)
; #pragma unroll
;                 for (int j = 0; j < 4; ++j) v[n][j] = silu(acc[ai][0][m][n][j] * r) * (acc[ai][1][m][n][j] * r);
;             *(u32x4*)(act + (size_t)row * FF + cb) = pack8(v[0], v[1]); }
	v_cvt_pk_bf16_f32 v50, v56, v57
	v_cvt_pk_bf16_f32 v51, v58, v59
	v_lshl_add_u64 v[52:53], v[52:53], 0, v[114:115]
	v_pk_mul_f32 v[46:47], v[46:47], v[154:155] op_sel_hi:[1,0]
	v_exp_f32_e64 v54, -v44
	v_exp_f32_e64 v55, -v45
	global_store_dwordx4 v[52:53], v[48:51], off
	v_pk_mul_f32 v[36:37], v[36:37], v[246:247] op_sel_hi:[1,0]
	v_pk_mul_f32 v[40:41], v[40:41], v[154:155] op_sel_hi:[1,0]
	v_exp_f32_e64 v50, -v46
	v_exp_f32_e64 v51, -v47
	v_add_f32_e32 v48, 1.0, v54
	v_add_f32_e32 v49, 1.0, v55
	v_rcp_f32_e32 v48, v48
	v_rcp_f32_e32 v49, v49
	v_add_f32_e32 v50, 1.0, v50
	v_add_f32_e32 v51, 1.0, v51
	v_rcp_f32_e32 v50, v50
	v_rcp_f32_e32 v51, v51
	v_pk_mul_f32 v[44:45], v[44:45], v[48:49]
	v_pk_mul_f32 v[38:39], v[38:39], v[246:247] op_sel_hi:[1,0]
	v_pk_mul_f32 v[36:37], v[36:37], v[44:45]
	v_pk_mul_f32 v[44:45], v[46:47], v[50:51]
	v_exp_f32_e64 v46, -v40
	v_exp_f32_e64 v47, -v41
	v_pk_mul_f32 v[42:43], v[42:43], v[154:155] op_sel_hi:[1,0]
	v_pk_mul_f32 v[38:39], v[38:39], v[44:45]
	v_add_f32_e32 v44, 1.0, v46
	v_add_f32_e32 v45, 1.0, v47
	v_exp_f32_e64 v46, -v42
	v_exp_f32_e64 v47, -v43
	v_rcp_f32_e32 v44, v44
	v_rcp_f32_e32 v45, v45
	v_add_f32_e32 v46, 1.0, v46
	v_add_f32_e32 v47, 1.0, v47
	v_rcp_f32_e32 v46, v46
	v_rcp_f32_e32 v47, v47
	v_pk_mul_f32 v[40:41], v[40:41], v[44:45]
	v_pk_mul_f32 v[32:33], v[32:33], v[246:247] op_sel_hi:[1,0]
	v_pk_mul_f32 v[34:35], v[34:35], v[246:247] op_sel_hi:[1,0]
	v_pk_mul_f32 v[40:41], v[32:33], v[40:41]
	v_pk_mul_f32 v[32:33], v[42:43], v[46:47]
	v_pk_mul_f32 v[28:29], v[28:29], v[150:151] op_sel_hi:[1,0]
	v_pk_mul_f32 v[42:43], v[34:35], v[32:33]
	v_cvt_pk_bf16_f32 v32, v36, v37
	v_mad_i64_i32 v[36:37], s[42:43], v152, s55, v[112:113]
	v_cvt_pk_bf16_f32 v33, v38, v39
	v_cvt_pk_bf16_f32 v34, v40, v41
	v_cvt_pk_bf16_f32 v35, v42, v43
	v_lshl_add_u64 v[36:37], v[36:37], 0, v[114:115]
	v_pk_mul_f32 v[30:31], v[30:31], v[150:151] op_sel_hi:[1,0]
	v_exp_f32_e64 v38, -v28
	v_exp_f32_e64 v39, -v29
	global_store_dwordx4 v[36:37], v[32:35], off
	v_pk_mul_f32 v[20:21], v[20:21], v[248:249] op_sel_hi:[1,0]
	v_pk_mul_f32 v[24:25], v[24:25], v[150:151] op_sel_hi:[1,0]
	v_exp_f32_e64 v34, -v30
	v_exp_f32_e64 v35, -v31
	v_add_f32_e32 v32, 1.0, v38
	v_add_f32_e32 v33, 1.0, v39
	v_rcp_f32_e32 v32, v32
	v_rcp_f32_e32 v33, v33
	v_add_f32_e32 v34, 1.0, v34
	v_add_f32_e32 v35, 1.0, v35
	v_rcp_f32_e32 v34, v34
	v_rcp_f32_e32 v35, v35
	v_pk_mul_f32 v[28:29], v[28:29], v[32:33]
	v_pk_mul_f32 v[22:23], v[22:23], v[248:249] op_sel_hi:[1,0]
	v_pk_mul_f32 v[20:21], v[20:21], v[28:29]
	v_pk_mul_f32 v[28:29], v[30:31], v[34:35]
	v_exp_f32_e64 v30, -v24
	v_exp_f32_e64 v31, -v25
	v_pk_mul_f32 v[26:27], v[26:27], v[150:151] op_sel_hi:[1,0]
	v_pk_mul_f32 v[22:23], v[22:23], v[28:29]
	v_add_f32_e32 v28, 1.0, v30
	v_add_f32_e32 v29, 1.0, v31
	v_exp_f32_e64 v30, -v26
	v_exp_f32_e64 v31, -v27
	v_rcp_f32_e32 v28, v28
	v_rcp_f32_e32 v29, v29
	v_add_f32_e32 v30, 1.0, v30
	v_add_f32_e32 v31, 1.0, v31
	v_rcp_f32_e32 v30, v30
	v_rcp_f32_e32 v31, v31
	v_pk_mul_f32 v[24:25], v[24:25], v[28:29]
	v_pk_mul_f32 v[16:17], v[16:17], v[248:249] op_sel_hi:[1,0]
	v_pk_mul_f32 v[18:19], v[18:19], v[248:249] op_sel_hi:[1,0]
	v_pk_mul_f32 v[24:25], v[16:17], v[24:25]
	v_pk_mul_f32 v[16:17], v[26:27], v[30:31]
	v_pk_mul_f32 v[12:13], v[12:13], v[146:147] op_sel_hi:[1,0]
	v_pk_mul_f32 v[26:27], v[18:19], v[16:17]
	v_cvt_pk_bf16_f32 v16, v20, v21
	v_mad_i64_i32 v[20:21], s[42:43], v148, s55, v[112:113]
	v_cvt_pk_bf16_f32 v17, v22, v23
	v_cvt_pk_bf16_f32 v18, v24, v25
	v_cvt_pk_bf16_f32 v19, v26, v27
	v_lshl_add_u64 v[20:21], v[20:21], 0, v[114:115]
	v_pk_mul_f32 v[14:15], v[14:15], v[146:147] op_sel_hi:[1,0]
	v_exp_f32_e64 v22, -v12
	v_exp_f32_e64 v23, -v13
	global_store_dwordx4 v[20:21], v[16:19], off
	v_pk_mul_f32 v[4:5], v[4:5], v[250:251] op_sel_hi:[1,0]
	v_pk_mul_f32 v[8:9], v[8:9], v[146:147] op_sel_hi:[1,0]
	v_exp_f32_e64 v18, -v14
	v_exp_f32_e64 v19, -v15
	v_add_f32_e32 v16, 1.0, v22
	v_add_f32_e32 v17, 1.0, v23
	v_rcp_f32_e32 v16, v16
	v_rcp_f32_e32 v17, v17
	v_add_f32_e32 v18, 1.0, v18
	v_add_f32_e32 v19, 1.0, v19
	v_rcp_f32_e32 v18, v18
	v_rcp_f32_e32 v19, v19
	v_pk_mul_f32 v[12:13], v[12:13], v[16:17]
	v_pk_mul_f32 v[6:7], v[6:7], v[250:251] op_sel_hi:[1,0]
	v_pk_mul_f32 v[4:5], v[4:5], v[12:13]
	v_pk_mul_f32 v[12:13], v[14:15], v[18:19]
	v_exp_f32_e64 v14, -v8
	v_exp_f32_e64 v15, -v9
	v_pk_mul_f32 v[10:11], v[10:11], v[146:147] op_sel_hi:[1,0]
	v_pk_mul_f32 v[6:7], v[6:7], v[12:13]
	v_add_f32_e32 v12, 1.0, v14
	v_add_f32_e32 v13, 1.0, v15
	v_exp_f32_e64 v14, -v10
	v_exp_f32_e64 v15, -v11
	v_rcp_f32_e32 v12, v12
	v_rcp_f32_e32 v13, v13
	v_add_f32_e32 v14, 1.0, v14
	v_add_f32_e32 v15, 1.0, v15
	v_rcp_f32_e32 v14, v14
	v_rcp_f32_e32 v15, v15
	v_pk_mul_f32 v[8:9], v[8:9], v[12:13]
	v_pk_mul_f32 v[0:1], v[0:1], v[250:251] op_sel_hi:[1,0]
	v_pk_mul_f32 v[2:3], v[2:3], v[250:251] op_sel_hi:[1,0]
	v_pk_mul_f32 v[8:9], v[0:1], v[8:9]
	v_pk_mul_f32 v[0:1], v[10:11], v[14:15]
	s_nop 0
	v_pk_mul_f32 v[10:11], v[2:3], v[0:1]
	v_cvt_pk_bf16_f32 v0, v4, v5
	v_mad_i64_i32 v[4:5], s[42:43], v144, s55, v[112:113]
	v_cvt_pk_bf16_f32 v1, v6, v7
	v_cvt_pk_bf16_f32 v2, v8, v9
	v_cvt_pk_bf16_f32 v3, v10, v11
	v_lshl_add_u64 v[4:5], v[4:5], 0, v[114:115]
	global_store_dwordx4 v[4:5], v[0:3], off
	s_cbranch_vccnz .LBB0_224
	s_andn2_b64 vcc, exec, s[10:11]
	s_cbranch_vccnz .LBB0_223
	s_barrier
	s_branch .LBB0_223

; #define PG8_STAGE(bufoff, gbase, voff) do { _Pragma("unroll") for (int _i = 0; _i < 2; ++_i) \
;         __builtin_amdgcn_global_load_lds((const unsigned*)((const char*)(gbase) + (voff)[_i]), (LAS unsigned*)(lds + (bufoff) + ldsw + _i * 8192), 16, 0, 0); } while (0)
; #define PG8_LDA(dst, b, h) do { _Pragma("unroll") for (int m = 0; m < 4; ++m) _Pragma("unroll") for (int k = 0; k < 2; ++k) dst[m][k] = *(const LAS bf16x8*)(lds + PG8_SA(b, h) + aoff + m * 2048 + k * 1024); } while (0)
; #define PG8_LDB(dst, b, h) do { _Pragma("unroll") for (int n = 0; n < 2; ++n) _Pragma("unroll") for (int k = 0; k < 2; ++k) dst[n][k] = *(const LAS bf16x8*)(lds + PG8_SB(b, h) + boff + n * 2048 + k * 1024); } while (0)
; #define PG8_MMA(ai, bj, At, Bt) do { __builtin_amdgcn_s_setprio(1); _Pragma("unroll") for (int m = 0; m < 4; ++m) _Pragma("unroll") for (int n = 0; n < 2; ++n) _Pragma("unroll") for (int k = 0; k < 2; ++k) \
;         acc[ai][bj][m][n] = __builtin_amdgcn_mfma_f32_16x16x32_bf16(Bt[n][k], At[m][k], acc[ai][bj][m][n], 0, 0, 0); __builtin_amdgcn_s_setprio(0); } while (0)
; #define PG8_WAIT_V(n) asm volatile("s_waitcnt vmcnt(" #n ")" ::: "memory")
; #define PG8_BAR __builtin_amdgcn_s_barrier()
; template <class Epi>
; DI void gemm_phase(LAS unsigned char* lds, const int wid, const Gemm g, const Order& S, const Epi& E) {
;     ...
;         const bool has_next = S.next(ui + 1, nxt);
;         const char* nA = has_next ? (const char*)(g.A + (size_t)nxt.g * g.gsA + (size_t)nxt.pm * BM * g.lda) : cA;
;         const char* nB = has_next ? (const char*)(g.Bt + (size_t)nxt.g * g.gsB + (size_t)nxt.pn * BM * g.ldb) : cB;
;         for (int t = 0; t < nt; t += 2) {
;             const bool last = (t == nt - 2);
;             const char* a1 = cA + (size_t)(t + 1) * kstep;
;             const char* a2 = last ? nA : cA + (size_t)(t + 2) * kstep; const char* b2 = last ? nB : cB + (size_t)(t + 2) * kstep;
;             const char* a3 = a2 + kstep; const char* b3 = b2 + kstep;
;             PG8_LDB(B0, 0, 0); PG8_LDB(B1, 0, 1); PG8_SCHED; PG8_LDA(At, 0, 0); PG8_STAGE(PG8_SA(1, 1), a1 + hstepA, voffA);
;             PG8_WAIT_V(8); PG8_WAIT_L(0); PG8_BAR; PG8_MMA(0, 0, At, B0); PG8_MMA(0, 1, At, B1); PG8_BAR; PG8_SCHED;
;             PG8_LDA(At, 0, 1); PG8_STAGE(PG8_SB(0, 0), b2, voffB); PG8_STAGE(PG8_SB(0, 1), b2 + hstepB, voffB); PG8_STAGE(PG8_SA(0, 0), a2, voffA);
.LBB0_1335:
	s_ashr_i32 s27, s26, 31
	s_lshl_b64 s[30:31], s[26:27], 19
	s_add_u32 s30, s6, s30
	s_addc_u32 s31, s7, s31
	s_and_b64 s[34:35], s[8:9], exec
	s_cselect_b32 s27, s31, s39
	s_cselect_b32 s56, s30, s38
	s_ashr_i32 s29, s28, 31
	s_lshl_b64 s[34:35], s[28:29], 19
	s_add_u32 s34, s21, s34
	s_addc_u32 s35, s44, s35
	s_and_b64 s[42:43], s[8:9], exec
	s_cselect_b32 s29, s35, s41
	s_cselect_b32 s57, s34, s40
	s_add_u32 s38, s38, 0x40080
	s_addc_u32 s39, s39, 0
	s_add_u32 s58, s40, 0x100
	v_mov_b32_e32 v0, 0
	s_addc_u32 s59, s41, 0
	s_mov_b32 s60, -2
	s_lshl_b32 s65, s36, 8
	s_add_i32 s65, s65, s95
	v_mbcnt_lo_u32_b32 v244, -1, 0
	v_mbcnt_hi_u32_b32 v244, -1, v244
	v_and_or_b32 v244, v244, 15, s65
	v_ashrrev_i32_e32 v245, 31, v244
	v_lshl_add_u64 v[246:247], v[244:245], 2, s[12:13]
	global_load_dword v236, v[246:247], off
	global_load_dword v237, v[246:247], off offset:64
	global_load_dword v238, v[246:247], off offset:128
	global_load_dword v239, v[246:247], off offset:192
	global_load_dword v240, v[246:247], off offset:512
	global_load_dword v241, v[246:247], off offset:576
	global_load_dword v242, v[246:247], off offset:640
	global_load_dword v243, v[246:247], off offset:704
	ds_read_b128 v[164:167], v151
	ds_read_b128 v[168:171], v151 offset:1024
	ds_read_b128 v[172:175], v151 offset:2048
	ds_read_b128 v[176:179], v151 offset:3072
	ds_read_b128 v[180:183], v155
	ds_read_b128 v[184:187], v155 offset:1024
	ds_read_b128 v[188:191], v155 offset:2048
	ds_read_b128 v[192:195], v155 offset:3072
	s_add_u32 s40, s38, 0xfffc0080
	s_addc_u32 s41, s39, -1
	s_cmp_eq_u32 s60, 12
	s_cselect_b32 s43, s27, s41
	s_cselect_b32 s42, s56, s40
	s_cselect_b32 s41, s29, s59
	s_cselect_b32 s40, s57, s58
	v_lshl_add_u64 v[144:145], s[38:39], 0, v[136:137]
	s_add_i32 m0, s37, 0xc000
	ds_read_b128 v[196:199], v159
	ds_read_b128 v[200:203], v159 offset:1024
	ds_read_b128 v[204:207], v159 offset:2048
	ds_read_b128 v[208:211], v159 offset:3072
	ds_read_b128 v[212:215], v159 offset:4096
	ds_read_b128 v[216:219], v159 offset:5120
	ds_read_b128 v[220:223], v159 offset:6144
	ds_read_b128 v[224:227], v159 offset:7168
	global_load_lds_dwordx4 v[144:145], off
	v_lshl_add_u64 v[144:145], s[38:39], 0, v[138:139]
	s_add_i32 m0, s37, 0xe000
	s_nop 0
	global_load_lds_dwordx4 v[144:145], off
	s_waitcnt vmcnt(8)
	s_waitcnt lgkmcnt(0)
	s_barrier
	s_setprio 1
	v_mfma_f32_16x16x32_bf16 v[124:127], v[164:167], v[196:199], 0
	v_mfma_f32_16x16x32_bf16 v[120:123], v[172:175], v[196:199], 0
	v_mfma_f32_16x16x32_bf16 v[108:111], v[164:167], v[204:207], 0
	v_mfma_f32_16x16x32_bf16 v[104:107], v[172:175], v[204:207], 0
	v_mfma_f32_16x16x32_bf16 v[92:95], v[164:167], v[212:215], 0
	v_mfma_f32_16x16x32_bf16 v[88:91], v[172:175], v[212:215], 0
	v_mfma_f32_16x16x32_bf16 v[76:79], v[164:167], v[220:223], 0
	v_mfma_f32_16x16x32_bf16 v[72:75], v[172:175], v[220:223], 0
	v_mfma_f32_16x16x32_bf16 v[124:127], v[168:171], v[200:203], v[124:127]
	v_mfma_f32_16x16x32_bf16 v[120:123], v[176:179], v[200:203], v[120:123]
	v_mfma_f32_16x16x32_bf16 v[108:111], v[168:171], v[208:211], v[108:111]
	v_mfma_f32_16x16x32_bf16 v[104:107], v[176:179], v[208:211], v[104:107]
	v_mfma_f32_16x16x32_bf16 v[92:95], v[168:171], v[216:219], v[92:95]
	v_mfma_f32_16x16x32_bf16 v[88:91], v[176:179], v[216:219], v[88:91]
	v_mfma_f32_16x16x32_bf16 v[76:79], v[168:171], v[224:227], v[76:79]
	v_mfma_f32_16x16x32_bf16 v[72:75], v[176:179], v[224:227], v[72:75]
	v_mfma_f32_16x16x32_bf16 v[116:119], v[180:183], v[196:199], 0
	v_mfma_f32_16x16x32_bf16 v[112:115], v[188:191], v[196:199], 0
	v_mfma_f32_16x16x32_bf16 v[100:103], v[180:183], v[204:207], 0
	v_mfma_f32_16x16x32_bf16 v[96:99], v[188:191], v[204:207], 0
	v_mfma_f32_16x16x32_bf16 v[84:87], v[180:183], v[212:215], 0
	v_mfma_f32_16x16x32_bf16 v[80:83], v[188:191], v[212:215], 0
	v_mfma_f32_16x16x32_bf16 v[68:71], v[180:183], v[220:223], 0
	v_mfma_f32_16x16x32_bf16 v[64:67], v[188:191], v[220:223], 0
	v_mfma_f32_16x16x32_bf16 v[116:119], v[184:187], v[200:203], v[116:119]
	v_mfma_f32_16x16x32_bf16 v[112:115], v[192:195], v[200:203], v[112:115]
	v_mfma_f32_16x16x32_bf16 v[100:103], v[184:187], v[208:211], v[100:103]
	v_mfma_f32_16x16x32_bf16 v[96:99], v[192:195], v[208:211], v[96:99]
	v_mfma_f32_16x16x32_bf16 v[84:87], v[184:187], v[216:219], v[84:87]
	v_mfma_f32_16x16x32_bf16 v[80:83], v[192:195], v[216:219], v[80:83]
	v_mfma_f32_16x16x32_bf16 v[68:71], v[184:187], v[224:227], v[68:71]
	v_mfma_f32_16x16x32_bf16 v[64:67], v[192:195], v[224:227], v[64:67]
	s_setprio 0
	s_barrier
	s_add_i32 s61, s53, s94
	v_lshl_add_u64 v[144:145], s[40:41], 0, v[132:133]
	s_mov_b32 m0, s61
	ds_read_b128 v[196:199], v159 offset:16384
	ds_read_b128 v[200:203], v159 offset:17408
	ds_read_b128 v[204:207], v159 offset:18432
	ds_read_b128 v[208:211], v159 offset:19456
	ds_read_b128 v[212:215], v159 offset:20480
	ds_read_b128 v[216:219], v159 offset:21504
	ds_read_b128 v[220:223], v159 offset:22528
	ds_read_b128 v[224:227], v159 offset:23552
	global_load_lds_dwordx4 v[144:145], off
	s_add_i32 m0, s61, 0x2000
	s_add_u32 s62, s40, 0x40000
	v_lshl_add_u64 v[148:149], s[40:41], 0, v[128:129]
	s_addc_u32 s63, s41, 0
	s_add_i32 s61, s54, s94
	global_load_lds_dwordx4 v[148:149], off
	v_lshl_add_u64 v[152:153], s[62:63], 0, v[132:133]
	s_mov_b32 m0, s61
	v_lshl_add_u64 v[156:157], s[42:43], 0, v[130:131]
	global_load_lds_dwordx4 v[152:153], off
	v_lshl_add_u64 v[152:153], s[62:63], 0, v[128:129]
	s_add_i32 m0, s61, 0x2000
	s_nop 0
	global_load_lds_dwordx4 v[152:153], off
	v_lshl_add_u64 v[152:153], s[42:43], 0, v[134:135]
	s_mov_b32 m0, s37
	s_nop 0
	global_load_lds_dwordx4 v[152:153], off
	s_mov_b32 m0, s46
	s_nop 0
	global_load_lds_dwordx4 v[156:157], off
	s_waitcnt vmcnt(8)
	s_waitcnt lgkmcnt(0)
	s_barrier
; #define PG8_STAGE(bufoff, gbase, voff) do { _Pragma("unroll") for (int _i = 0; _i < 2; ++_i) \
;         __builtin_amdgcn_global_load_lds((const unsigned*)((const char*)(gbase) + (voff)[_i]), (LAS unsigned*)(lds + (bufoff) + ldsw + _i * 8192), 16, 0, 0); } while (0)
; #define PG8_LDA(dst, b, h) do { _Pragma("unroll") for (int m = 0; m < 4; ++m) _Pragma("unroll") for (int k = 0; k < 2; ++k) dst[m][k] = *(const LAS bf16x8*)(lds + PG8_SA(b, h) + aoff + m * 2048 + k * 1024); } while (0)
; #define PG8_LDB(dst, b, h) do { _Pragma("unroll") for (int n = 0; n < 2; ++n) _Pragma("unroll") for (int k = 0; k < 2; ++k) dst[n][k] = *(const LAS bf16x8*)(lds + PG8_SB(b, h) + boff + n * 2048 + k * 1024); } while (0)
; #define PG8_MMA(ai, bj, At, Bt) do { __builtin_amdgcn_s_setprio(1); _Pragma("unroll") for (int m = 0; m < 4; ++m) _Pragma("unroll") for (int n = 0; n < 2; ++n) _Pragma("unroll") for (int k = 0; k < 2; ++k) \
;         acc[ai][bj][m][n] = __builtin_amdgcn_mfma_f32_16x16x32_bf16(Bt[n][k], At[m][k], acc[ai][bj][m][n], 0, 0, 0); __builtin_amdgcn_s_setprio(0); } while (0)
; #define PG8_WAIT_V(n) asm volatile("s_waitcnt vmcnt(" #n ")" ::: "memory")
; #define PG8_WAIT_L(n) asm volatile("s_waitcnt lgkmcnt(" #n ")" ::: "memory")
; #define PG8_BAR __builtin_amdgcn_s_barrier()
; #define PG8_SCHED __builtin_amdgcn_sched_barrier(0)
; template <class Epi>
; DI void gemm_phase(LAS unsigned char* lds, const int wid, const Gemm g, const Order& S, const Epi& E) {
;     ...
;             PG8_WAIT_V(8); PG8_WAIT_L(0); PG8_BAR; PG8_MMA(1, 0, At, B0); PG8_MMA(1, 1, At, B1); PG8_BAR; PG8_SCHED;
;             PG8_LDB(B0, 1, 0); PG8_LDB(B1, 1, 1); PG8_SCHED; PG8_LDA(At, 1, 0); PG8_STAGE(PG8_SA(0, 1), a2 + hstepA, voffA);
;             PG8_WAIT_V(8); PG8_WAIT_L(0); PG8_BAR; PG8_MMA(0, 0, At, B0); PG8_MMA(0, 1, At, B1); PG8_BAR; PG8_SCHED;
	s_setprio 1
	v_mfma_f32_16x16x32_bf16 v[60:63], v[164:167], v[196:199], 0
	v_mfma_f32_16x16x32_bf16 v[56:59], v[172:175], v[196:199], 0
	v_mfma_f32_16x16x32_bf16 v[44:47], v[164:167], v[204:207], 0
	v_mfma_f32_16x16x32_bf16 v[40:43], v[172:175], v[204:207], 0
	v_mfma_f32_16x16x32_bf16 v[28:31], v[164:167], v[212:215], 0
	v_mfma_f32_16x16x32_bf16 v[24:27], v[172:175], v[212:215], 0
	v_mfma_f32_16x16x32_bf16 v[12:15], v[164:167], v[220:223], 0
	v_mfma_f32_16x16x32_bf16 v[8:11], v[172:175], v[220:223], 0
	v_mfma_f32_16x16x32_bf16 v[60:63], v[168:171], v[200:203], v[60:63]
	v_mfma_f32_16x16x32_bf16 v[56:59], v[176:179], v[200:203], v[56:59]
	v_mfma_f32_16x16x32_bf16 v[44:47], v[168:171], v[208:211], v[44:47]
	v_mfma_f32_16x16x32_bf16 v[40:43], v[176:179], v[208:211], v[40:43]
	v_mfma_f32_16x16x32_bf16 v[28:31], v[168:171], v[216:219], v[28:31]
	v_mfma_f32_16x16x32_bf16 v[24:27], v[176:179], v[216:219], v[24:27]
	v_mfma_f32_16x16x32_bf16 v[12:15], v[168:171], v[224:227], v[12:15]
	v_mfma_f32_16x16x32_bf16 v[8:11], v[176:179], v[224:227], v[8:11]
	v_mfma_f32_16x16x32_bf16 v[52:55], v[180:183], v[196:199], 0
	v_mfma_f32_16x16x32_bf16 v[48:51], v[188:191], v[196:199], 0
	v_mfma_f32_16x16x32_bf16 v[36:39], v[180:183], v[204:207], 0
	v_mfma_f32_16x16x32_bf16 v[32:35], v[188:191], v[204:207], 0
	v_mfma_f32_16x16x32_bf16 v[20:23], v[180:183], v[212:215], 0
	v_mfma_f32_16x16x32_bf16 v[16:19], v[188:191], v[212:215], 0
	v_mfma_f32_16x16x32_bf16 v[4:7], v[180:183], v[220:223], 0
	v_mfma_f32_16x16x32_bf16 v[0:3], v[188:191], v[220:223], 0
	v_mfma_f32_16x16x32_bf16 v[52:55], v[184:187], v[200:203], v[52:55]
	v_mfma_f32_16x16x32_bf16 v[48:51], v[192:195], v[200:203], v[48:51]
	v_mfma_f32_16x16x32_bf16 v[36:39], v[184:187], v[208:211], v[36:39]
	v_mfma_f32_16x16x32_bf16 v[32:35], v[192:195], v[208:211], v[32:35]
	v_mfma_f32_16x16x32_bf16 v[20:23], v[184:187], v[216:219], v[20:23]
	v_mfma_f32_16x16x32_bf16 v[16:19], v[192:195], v[216:219], v[16:19]
	v_mfma_f32_16x16x32_bf16 v[4:7], v[184:187], v[224:227], v[4:7]
	v_mfma_f32_16x16x32_bf16 v[0:3], v[192:195], v[224:227], v[0:3]
	s_setprio 0
	s_barrier
	s_add_i32 s61, 0, 0x18000
	v_add_u32_e32 v146, s61, v147
	s_add_i32 s62, 0, 0x1c000
	ds_read_b128 v[164:167], v146
	ds_read_b128 v[168:171], v146 offset:1024
	ds_read_b128 v[172:175], v146 offset:2048
	ds_read_b128 v[176:179], v146 offset:3072
	v_add_u32_e32 v146, s62, v147
	ds_read_b128 v[180:183], v146
	ds_read_b128 v[184:187], v146 offset:1024
	ds_read_b128 v[188:191], v146 offset:2048
	ds_read_b128 v[192:195], v146 offset:3072
	s_add_u32 s42, s42, 0x40000
	s_addc_u32 s43, s43, 0
	s_mov_b32 m0, s47
	v_lshl_add_u64 v[160:161], s[42:43], 0, v[134:135]
	ds_read_b128 v[196:199], v159 offset:32768
	ds_read_b128 v[200:203], v159 offset:33792
	ds_read_b128 v[204:207], v159 offset:34816
	ds_read_b128 v[208:211], v159 offset:35840
	ds_read_b128 v[212:215], v159 offset:36864
	ds_read_b128 v[216:219], v159 offset:37888
	ds_read_b128 v[220:223], v159 offset:38912
	ds_read_b128 v[224:227], v159 offset:39936
	global_load_lds_dwordx4 v[160:161], off
	v_lshl_add_u64 v[160:161], s[42:43], 0, v[130:131]
	s_mov_b32 m0, s48
	s_nop 0
	global_load_lds_dwordx4 v[160:161], off
	s_waitcnt vmcnt(8)
	s_waitcnt lgkmcnt(0)
	s_barrier
	s_setprio 1
	v_mfma_f32_16x16x32_bf16 v[124:127], v[164:167], v[196:199], v[124:127]
	v_mfma_f32_16x16x32_bf16 v[120:123], v[172:175], v[196:199], v[120:123]
	v_mfma_f32_16x16x32_bf16 v[108:111], v[164:167], v[204:207], v[108:111]
	v_mfma_f32_16x16x32_bf16 v[104:107], v[172:175], v[204:207], v[104:107]
	v_mfma_f32_16x16x32_bf16 v[92:95], v[164:167], v[212:215], v[92:95]
	v_mfma_f32_16x16x32_bf16 v[88:91], v[172:175], v[212:215], v[88:91]
	v_mfma_f32_16x16x32_bf16 v[76:79], v[164:167], v[220:223], v[76:79]
	v_mfma_f32_16x16x32_bf16 v[72:75], v[172:175], v[220:223], v[72:75]
	v_mfma_f32_16x16x32_bf16 v[124:127], v[168:171], v[200:203], v[124:127]
	v_mfma_f32_16x16x32_bf16 v[120:123], v[176:179], v[200:203], v[120:123]
	v_mfma_f32_16x16x32_bf16 v[108:111], v[168:171], v[208:211], v[108:111]
	v_mfma_f32_16x16x32_bf16 v[104:107], v[176:179], v[208:211], v[104:107]
	v_mfma_f32_16x16x32_bf16 v[92:95], v[168:171], v[216:219], v[92:95]
	v_mfma_f32_16x16x32_bf16 v[88:91], v[176:179], v[216:219], v[88:91]
	v_mfma_f32_16x16x32_bf16 v[76:79], v[168:171], v[224:227], v[76:79]
	v_mfma_f32_16x16x32_bf16 v[72:75], v[176:179], v[224:227], v[72:75]
	v_mfma_f32_16x16x32_bf16 v[116:119], v[180:183], v[196:199], v[116:119]
	v_mfma_f32_16x16x32_bf16 v[112:115], v[188:191], v[196:199], v[112:115]
	v_mfma_f32_16x16x32_bf16 v[100:103], v[180:183], v[204:207], v[100:103]
	v_mfma_f32_16x16x32_bf16 v[96:99], v[188:191], v[204:207], v[96:99]
	v_mfma_f32_16x16x32_bf16 v[84:87], v[180:183], v[212:215], v[84:87]
	v_mfma_f32_16x16x32_bf16 v[80:83], v[188:191], v[212:215], v[80:83]
	v_mfma_f32_16x16x32_bf16 v[68:71], v[180:183], v[220:223], v[68:71]
	v_mfma_f32_16x16x32_bf16 v[64:67], v[188:191], v[220:223], v[64:67]
	v_mfma_f32_16x16x32_bf16 v[116:119], v[184:187], v[200:203], v[116:119]
	v_mfma_f32_16x16x32_bf16 v[112:115], v[192:195], v[200:203], v[112:115]
	v_mfma_f32_16x16x32_bf16 v[100:103], v[184:187], v[208:211], v[100:103]
	v_mfma_f32_16x16x32_bf16 v[96:99], v[192:195], v[208:211], v[96:99]
	v_mfma_f32_16x16x32_bf16 v[84:87], v[184:187], v[216:219], v[84:87]
	v_mfma_f32_16x16x32_bf16 v[80:83], v[192:195], v[216:219], v[80:83]
	v_mfma_f32_16x16x32_bf16 v[68:71], v[184:187], v[224:227], v[68:71]
	v_mfma_f32_16x16x32_bf16 v[64:67], v[192:195], v[224:227], v[64:67]
	s_setprio 0
	s_barrier
; #define PG8_STAGE(bufoff, gbase, voff) do { _Pragma("unroll") for (int _i = 0; _i < 2; ++_i) \
;         __builtin_amdgcn_global_load_lds((const unsigned*)((const char*)(gbase) + (voff)[_i]), (LAS unsigned*)(lds + (bufoff) + ldsw + _i * 8192), 16, 0, 0); } while (0)
; #define PG8_LDA(dst, b, h) do { _Pragma("unroll") for (int m = 0; m < 4; ++m) _Pragma("unroll") for (int k = 0; k < 2; ++k) dst[m][k] = *(const LAS bf16x8*)(lds + PG8_SA(b, h) + aoff + m * 2048 + k * 1024); } while (0)
; #define PG8_MMA(ai, bj, At, Bt) do { __builtin_amdgcn_s_setprio(1); _Pragma("unroll") for (int m = 0; m < 4; ++m) _Pragma("unroll") for (int n = 0; n < 2; ++n) _Pragma("unroll") for (int k = 0; k < 2; ++k) \
;         acc[ai][bj][m][n] = __builtin_amdgcn_mfma_f32_16x16x32_bf16(Bt[n][k], At[m][k], acc[ai][bj][m][n], 0, 0, 0); __builtin_amdgcn_s_setprio(0); } while (0)
; #define PG8_WAIT_V(n) asm volatile("s_waitcnt vmcnt(" #n ")" ::: "memory")
; #define PG8_WAIT_L(n) asm volatile("s_waitcnt lgkmcnt(" #n ")" ::: "memory")
; #define PG8_BAR __builtin_amdgcn_s_barrier()
; #define PG8_SCHED __builtin_amdgcn_sched_barrier(0)
; template <class Epi>
; DI void gemm_phase(LAS unsigned char* lds, const int wid, const Gemm g, const Order& S, const Epi& E) {
;     ...
;             PG8_LDA(At, 1, 1); PG8_STAGE(PG8_SB(1, 0), b3, voffB); PG8_STAGE(PG8_SB(1, 1), b3 + hstepB, voffB); PG8_STAGE(PG8_SA(1, 0), a3, voffA);
;             PG8_WAIT_V(8); PG8_WAIT_L(0); PG8_BAR; PG8_MMA(1, 0, At, B0); PG8_MMA(1, 1, At, B1); PG8_BAR; PG8_SCHED;
;         }
	s_add_i32 s42, s61, s94
	v_lshl_add_u64 v[144:145], v[144:145], 0, s[16:17]
	s_mov_b32 m0, s42
	ds_read_b128 v[196:199], v159 offset:49152
	ds_read_b128 v[200:203], v159 offset:50176
	ds_read_b128 v[204:207], v159 offset:51200
	ds_read_b128 v[208:211], v159 offset:52224
	ds_read_b128 v[212:215], v159 offset:53248
	ds_read_b128 v[216:219], v159 offset:54272
	ds_read_b128 v[220:223], v159 offset:55296
	ds_read_b128 v[224:227], v159 offset:56320
	global_load_lds_dwordx4 v[144:145], off
	s_add_i32 m0, s42, 0x2000
	s_add_u32 s40, s40, 0x40080
	v_lshl_add_u64 v[144:145], v[148:149], 0, s[16:17]
	s_addc_u32 s41, s41, 0
	s_add_i32 s42, s62, s94
	global_load_lds_dwordx4 v[144:145], off
	v_lshl_add_u64 v[144:145], s[40:41], 0, v[132:133]
	s_mov_b32 m0, s42
	s_nop 0
	global_load_lds_dwordx4 v[144:145], off
	v_lshl_add_u64 v[144:145], s[40:41], 0, v[128:129]
	s_add_i32 m0, s42, 0x2000
	s_nop 0
	global_load_lds_dwordx4 v[144:145], off
	v_lshl_add_u64 v[144:145], v[152:153], 0, s[16:17]
	s_mov_b32 m0, s51
	s_nop 0
	global_load_lds_dwordx4 v[144:145], off
	v_lshl_add_u64 v[144:145], v[156:157], 0, s[16:17]
	s_mov_b32 m0, s52
	s_nop 0
	global_load_lds_dwordx4 v[144:145], off
	s_waitcnt vmcnt(8)
	s_waitcnt lgkmcnt(0)
	s_barrier
	s_setprio 1
	v_mfma_f32_16x16x32_bf16 v[60:63], v[164:167], v[196:199], v[60:63]
	v_mfma_f32_16x16x32_bf16 v[56:59], v[172:175], v[196:199], v[56:59]
	v_mfma_f32_16x16x32_bf16 v[44:47], v[164:167], v[204:207], v[44:47]
	v_mfma_f32_16x16x32_bf16 v[40:43], v[172:175], v[204:207], v[40:43]
	v_mfma_f32_16x16x32_bf16 v[28:31], v[164:167], v[212:215], v[28:31]
	v_mfma_f32_16x16x32_bf16 v[24:27], v[172:175], v[212:215], v[24:27]
	v_mfma_f32_16x16x32_bf16 v[12:15], v[164:167], v[220:223], v[12:15]
	v_mfma_f32_16x16x32_bf16 v[8:11], v[172:175], v[220:223], v[8:11]
	v_mfma_f32_16x16x32_bf16 v[60:63], v[168:171], v[200:203], v[60:63]
	v_mfma_f32_16x16x32_bf16 v[56:59], v[176:179], v[200:203], v[56:59]
	v_mfma_f32_16x16x32_bf16 v[44:47], v[168:171], v[208:211], v[44:47]
	v_mfma_f32_16x16x32_bf16 v[40:43], v[176:179], v[208:211], v[40:43]
	v_mfma_f32_16x16x32_bf16 v[28:31], v[168:171], v[216:219], v[28:31]
	v_mfma_f32_16x16x32_bf16 v[24:27], v[176:179], v[216:219], v[24:27]
	v_mfma_f32_16x16x32_bf16 v[12:15], v[168:171], v[224:227], v[12:15]
	v_mfma_f32_16x16x32_bf16 v[8:11], v[176:179], v[224:227], v[8:11]
	v_mfma_f32_16x16x32_bf16 v[52:55], v[180:183], v[196:199], v[52:55]
	v_mfma_f32_16x16x32_bf16 v[48:51], v[188:191], v[196:199], v[48:51]
	v_mfma_f32_16x16x32_bf16 v[36:39], v[180:183], v[204:207], v[36:39]
	v_mfma_f32_16x16x32_bf16 v[32:35], v[188:191], v[204:207], v[32:35]
	v_mfma_f32_16x16x32_bf16 v[20:23], v[180:183], v[212:215], v[20:23]
	v_mfma_f32_16x16x32_bf16 v[16:19], v[188:191], v[212:215], v[16:19]
	v_mfma_f32_16x16x32_bf16 v[4:7], v[180:183], v[220:223], v[4:7]
	v_mfma_f32_16x16x32_bf16 v[0:3], v[188:191], v[220:223], v[0:3]
	v_mfma_f32_16x16x32_bf16 v[52:55], v[184:187], v[200:203], v[52:55]
	v_mfma_f32_16x16x32_bf16 v[48:51], v[192:195], v[200:203], v[48:51]
	v_mfma_f32_16x16x32_bf16 v[36:39], v[184:187], v[208:211], v[36:39]
	v_mfma_f32_16x16x32_bf16 v[32:35], v[192:195], v[208:211], v[32:35]
	v_mfma_f32_16x16x32_bf16 v[20:23], v[184:187], v[216:219], v[20:23]
	v_mfma_f32_16x16x32_bf16 v[16:19], v[192:195], v[216:219], v[16:19]
	v_mfma_f32_16x16x32_bf16 v[4:7], v[184:187], v[224:227], v[4:7]
	v_mfma_f32_16x16x32_bf16 v[0:3], v[192:195], v[224:227], v[0:3]
	s_setprio 0
	s_barrier
	s_add_i32 s60, s60, 2
	s_add_u32 s38, s38, 0x100
	s_addc_u32 s39, s39, 0
	s_add_u32 s58, s58, 0x100
	s_addc_u32 s59, s59, 0
	s_cmp_gt_u32 s60, 13
	s_cbranch_scc0 .LBB0_1336
	s_branch .Lpeel_exit_9

; DI float silu(float x) { return x * sigm(x); }
; DI u32x4 pack8(f32x4 a, f32x4 b) { u32x4 w; w.x = pk2(a[0], a[1]); w.y = pk2(a[2], a[3]); w.z = pk2(b[0], b[1]); w.w = pk2(b[2], b[3]); return w; }
; #define EPI_ROWS(ai, m) _Pragma("unroll") for (int ai = 0; ai < 2; ++ai) _Pragma("unroll") for (int m = 0; m < 4; ++m)
; #define EPI_RSTD8(rr, ssqp, invn) float rr[2][4]; EPI_ROWS(ai, m) rr[ai][m] = (ssqp)[epi_row(u, ai, wr, m, fr)]; EPI_FENCE(); EPI_ROWS(ai, m) rr[ai][m] = rstd_of(rr[ai][m], invn);
; DI float rstd_of(float ssq, float invn) { return __builtin_amdgcn_rsqf(ssq * invn + EPS); }
;     DI void operator()(const Acc& acc, const Unit& u, int wr, int wc, int fr, int fq) const {
;         const int cb = u.pn * 128 + wc * 32 + 8 * fq;
;         EPI_RSTD8(rr, ssq, 1.0f / D)
;         EPI_ROWS(ai, m) { const int row = epi_row(u, ai, wr, m, fr); const float r = rr[ai][m];
;             f32x4 v[2];
; #pragma unroll
;             for (int n = 0; n < 2; ++n)
; #pragma unroll
;                 for (int j = 0; j < 4; ++j) v[n][j] = silu(acc[ai][0][m][n][j] * r) * (acc[ai][1][m][n][j] * r);
;             *(u32x4*)(act + (size_t)row * FF + cb) = pack8(v[0], v[1]); }
.LBB0_1339:
	s_lshl_b32 s27, s36, 8
	s_add_i32 s27, s27, s95
	v_mbcnt_lo_u32_b32 v146, -1, 0
	v_mbcnt_hi_u32_b32 v146, -1, v146
	s_andn2_b64 vcc, exec, s[8:9]
	v_and_or_b32 v170, v146, 15, s27
	v_ashrrev_i32_e32 v171, 31, v170
	v_or_b32_e32 v168, 16, v170
	v_ashrrev_i32_e32 v169, 31, v168
	v_or_b32_e32 v164, 32, v170
	v_or_b32_e32 v160, 48, v170
	v_add_u32_e32 v156, 0x80, v170
	v_add_u32_e32 v152, 0x90, v170
	v_add_u32_e32 v148, 0xa0, v170
	v_add_u32_e32 v144, 0xb0, v170
	v_ashrrev_i32_e32 v165, 31, v164
	v_ashrrev_i32_e32 v161, 31, v160
	v_ashrrev_i32_e32 v157, 31, v156
	v_ashrrev_i32_e32 v153, 31, v152
	v_ashrrev_i32_e32 v149, 31, v148
	v_ashrrev_i32_e32 v145, 31, v144
	s_lshl_b32 s27, s55, 7
	v_ashrrev_i32_e32 v146, 1, v146
	s_or_b32 s27, s27, s22
	v_and_b32_e32 v146, -8, v146
	v_add_u32_e32 v172, s27, v146
	v_ashrrev_i32_e32 v173, 31, v172
	s_mov_b64 s[8:9], -1
	s_waitcnt vmcnt(8)
	v_fmamk_f32 v146, v236, 0x3a800000, v163
	v_rsq_f32_e32 v174, v146
	v_fmamk_f32 v145, v237, 0x3a800000, v163
	v_fmamk_f32 v146, v238, 0x3a800000, v163
	v_fmamk_f32 v149, v239, 0x3a800000, v163
	v_fmamk_f32 v150, v240, 0x3a800000, v163
	v_fmamk_f32 v153, v241, 0x3a800000, v163
	v_fmamk_f32 v157, v242, 0x3a800000, v163
	v_fmamk_f32 v161, v243, 0x3a800000, v163
	v_mul_f32_e32 v236, 0x3f317218, v174
	v_mul_f32_e32 v174, 0x3fb8aa3b, v174
	v_pk_mul_f32 v[124:125], v[124:125], v[174:175] op_sel_hi:[1,0]
	v_pk_mul_f32 v[126:127], v[126:127], v[174:175] op_sel_hi:[1,0]
	v_pk_mul_f32 v[120:121], v[120:121], v[174:175] op_sel_hi:[1,0]
	v_rsq_f32_e32 v176, v145
	v_rsq_f32_e32 v166, v146
	v_rsq_f32_e32 v162, v149
	v_rsq_f32_e32 v158, v150
	v_rsq_f32_e32 v154, v153
	v_rsq_f32_e32 v150, v157
	v_rsq_f32_e32 v146, v161
	s_nop 0
	v_mul_f32_e32 v238, 0x3f317218, v176
	v_mul_f32_e32 v240, 0x3f317218, v166
	v_mul_f32_e32 v242, 0x3f317218, v162
	v_mul_f32_e32 v244, 0x3f317218, v158
	v_mul_f32_e32 v246, 0x3f317218, v154
	v_mul_f32_e32 v248, 0x3f317218, v150
	v_mul_f32_e32 v250, 0x3f317218, v146
	v_mul_f32_e32 v176, 0x3fb8aa3b, v176
	v_mul_f32_e32 v166, 0x3fb8aa3b, v166
	v_mul_f32_e32 v162, 0x3fb8aa3b, v162
	v_mul_f32_e32 v158, 0x3fb8aa3b, v158
	v_mul_f32_e32 v154, 0x3fb8aa3b, v154
	v_mul_f32_e32 v150, 0x3fb8aa3b, v150
	v_mul_f32_e32 v146, 0x3fb8aa3b, v146
	v_pk_mul_f32 v[122:123], v[122:123], v[174:175] op_sel_hi:[1,0]
	v_exp_f32_e64 v145, -v124
	v_exp_f32_e64 v149, -v125
	v_exp_f32_e64 v153, -v126
	v_exp_f32_e64 v157, -v127
	v_exp_f32_e64 v161, -v120
	v_exp_f32_e64 v165, -v121
	v_exp_f32_e64 v167, -v122
	v_exp_f32_e64 v169, -v123
	v_add_f32_e32 v145, 1.0, v145
	v_add_f32_e32 v149, 1.0, v149
	v_add_f32_e32 v153, 1.0, v153
	v_add_f32_e32 v157, 1.0, v157
	v_add_f32_e32 v161, 1.0, v161
	v_add_f32_e32 v165, 1.0, v165
	v_add_f32_e32 v167, 1.0, v167
	v_add_f32_e32 v169, 1.0, v169
	v_rcp_f32_e32 v178, v145
	v_rcp_f32_e32 v179, v149
	v_rcp_f32_e32 v180, v153
	v_rcp_f32_e32 v181, v157
	v_rcp_f32_e32 v182, v161
	v_rcp_f32_e32 v183, v165
	v_rcp_f32_e32 v184, v167
	v_rcp_f32_e32 v185, v169
	v_pk_mul_f32 v[116:117], v[116:117], v[236:237] op_sel_hi:[1,0]
	v_pk_mul_f32 v[118:119], v[118:119], v[236:237] op_sel_hi:[1,0]
	v_pk_mul_f32 v[112:113], v[112:113], v[236:237] op_sel_hi:[1,0]
	v_pk_mul_f32 v[124:125], v[124:125], v[178:179]
	v_pk_mul_f32 v[126:127], v[126:127], v[180:181]
	v_pk_mul_f32 v[120:121], v[120:121], v[182:183]
	v_pk_mul_f32 v[116:117], v[116:117], v[124:125]
	v_pk_mul_f32 v[118:119], v[118:119], v[126:127]
	v_pk_mul_f32 v[112:113], v[112:113], v[120:121]
	v_pk_mul_f32 v[120:121], v[122:123], v[184:185]
	v_pk_mul_f32 v[114:115], v[114:115], v[236:237] op_sel_hi:[1,0]
	v_cvt_pk_bf16_f32 v116, v116, v117
	v_pk_mul_f32 v[114:115], v[114:115], v[120:121]
	v_cvt_pk_bf16_f32 v117, v118, v119
	v_cvt_pk_bf16_f32 v118, v112, v113
	v_mov_b64_e32 v[112:113], s[14:15]
	v_cvt_pk_bf16_f32 v119, v114, v115
	v_mad_i64_i32 v[120:121], s[38:39], v170, s49, v[112:113]
	v_lshlrev_b64 v[114:115], 1, v[172:173]
	v_pk_mul_f32 v[108:109], v[108:109], v[176:177] op_sel_hi:[1,0]
	v_lshl_add_u64 v[120:121], v[120:121], 0, v[114:115]
	v_pk_mul_f32 v[110:111], v[110:111], v[176:177] op_sel_hi:[1,0]
	v_exp_f32_e64 v122, -v108
	v_exp_f32_e64 v123, -v109
	global_store_dwordx4 v[120:121], v[116:119], off
	v_pk_mul_f32 v[100:101], v[100:101], v[238:239] op_sel_hi:[1,0]
	v_pk_mul_f32 v[104:105], v[104:105], v[176:177] op_sel_hi:[1,0]
	v_exp_f32_e64 v118, -v110
	v_exp_f32_e64 v119, -v111
	v_add_f32_e32 v116, 1.0, v122
	v_add_f32_e32 v117, 1.0, v123
	v_rcp_f32_e32 v116, v116
	v_rcp_f32_e32 v117, v117
	v_add_f32_e32 v118, 1.0, v118
	v_add_f32_e32 v119, 1.0, v119
	v_rcp_f32_e32 v118, v118
	v_rcp_f32_e32 v119, v119
	v_pk_mul_f32 v[108:109], v[108:109], v[116:117]
	v_pk_mul_f32 v[102:103], v[102:103], v[238:239] op_sel_hi:[1,0]
	v_pk_mul_f32 v[100:101], v[100:101], v[108:109]
	v_pk_mul_f32 v[108:109], v[110:111], v[118:119]
	v_exp_f32_e64 v110, -v104
	v_exp_f32_e64 v111, -v105
	v_pk_mul_f32 v[106:107], v[106:107], v[176:177] op_sel_hi:[1,0]
	v_pk_mul_f32 v[102:103], v[102:103], v[108:109]
	v_add_f32_e32 v108, 1.0, v110
	v_add_f32_e32 v109, 1.0, v111
	v_exp_f32_e64 v110, -v106
	v_exp_f32_e64 v111, -v107
	v_rcp_f32_e32 v108, v108
	v_rcp_f32_e32 v109, v109
	v_add_f32_e32 v110, 1.0, v110
	v_add_f32_e32 v111, 1.0, v111
	v_rcp_f32_e32 v110, v110
	v_rcp_f32_e32 v111, v111
	v_pk_mul_f32 v[104:105], v[104:105], v[108:109]
	v_pk_mul_f32 v[96:97], v[96:97], v[238:239] op_sel_hi:[1,0]
	v_pk_mul_f32 v[98:99], v[98:99], v[238:239] op_sel_hi:[1,0]
	v_pk_mul_f32 v[104:105], v[96:97], v[104:105]
	v_pk_mul_f32 v[96:97], v[106:107], v[110:111]
	v_pk_mul_f32 v[92:93], v[92:93], v[166:167] op_sel_hi:[1,0]
	v_pk_mul_f32 v[106:107], v[98:99], v[96:97]
; DI float silu(float x) { return x * sigm(x); }
; DI u32x4 pack8(f32x4 a, f32x4 b) { u32x4 w; w.x = pk2(a[0], a[1]); w.y = pk2(a[2], a[3]); w.z = pk2(b[0], b[1]); w.w = pk2(b[2], b[3]); return w; }
; #define EPI_ROWS(ai, m) _Pragma("unroll") for (int ai = 0; ai < 2; ++ai) _Pragma("unroll") for (int m = 0; m < 4; ++m)
;     DI void operator()(const Acc& acc, const Unit& u, int wr, int wc, int fr, int fq) const {
;     ...
;         EPI_ROWS(ai, m) { const int row = epi_row(u, ai, wr, m, fr); const float r = rr[ai][m];
;             f32x4 v[2];
; #pragma unroll
;             for (int n = 0; n < 2; ++n)
; #pragma unroll
;                 for (int j = 0; j < 4; ++j) v[n][j] = silu(acc[ai][0][m][n][j] * r) * (acc[ai][1][m][n][j] * r);
;             *(u32x4*)(act + (size_t)row * FF + cb) = pack8(v[0], v[1]); }
	v_cvt_pk_bf16_f32 v96, v100, v101
	v_mad_i64_i32 v[100:101], s[38:39], v168, s49, v[112:113]
	v_cvt_pk_bf16_f32 v97, v102, v103
	v_cvt_pk_bf16_f32 v98, v104, v105
	v_cvt_pk_bf16_f32 v99, v106, v107
	v_lshl_add_u64 v[100:101], v[100:101], 0, v[114:115]
	v_pk_mul_f32 v[94:95], v[94:95], v[166:167] op_sel_hi:[1,0]
	v_exp_f32_e64 v102, -v92
	v_exp_f32_e64 v103, -v93
	global_store_dwordx4 v[100:101], v[96:99], off
	v_pk_mul_f32 v[84:85], v[84:85], v[240:241] op_sel_hi:[1,0]
	v_pk_mul_f32 v[88:89], v[88:89], v[166:167] op_sel_hi:[1,0]
	v_exp_f32_e64 v98, -v94
	v_exp_f32_e64 v99, -v95
	v_add_f32_e32 v96, 1.0, v102
	v_add_f32_e32 v97, 1.0, v103
	v_rcp_f32_e32 v96, v96
	v_rcp_f32_e32 v97, v97
	v_add_f32_e32 v98, 1.0, v98
	v_add_f32_e32 v99, 1.0, v99
	v_rcp_f32_e32 v98, v98
	v_rcp_f32_e32 v99, v99
	v_pk_mul_f32 v[92:93], v[92:93], v[96:97]
	v_pk_mul_f32 v[86:87], v[86:87], v[240:241] op_sel_hi:[1,0]
	v_pk_mul_f32 v[84:85], v[84:85], v[92:93]
	v_pk_mul_f32 v[92:93], v[94:95], v[98:99]
	v_exp_f32_e64 v94, -v88
	v_exp_f32_e64 v95, -v89
	v_pk_mul_f32 v[90:91], v[90:91], v[166:167] op_sel_hi:[1,0]
	v_pk_mul_f32 v[86:87], v[86:87], v[92:93]
	v_add_f32_e32 v92, 1.0, v94
	v_add_f32_e32 v93, 1.0, v95
	v_exp_f32_e64 v94, -v90
	v_exp_f32_e64 v95, -v91
	v_rcp_f32_e32 v92, v92
	v_rcp_f32_e32 v93, v93
	v_add_f32_e32 v94, 1.0, v94
	v_add_f32_e32 v95, 1.0, v95
	v_rcp_f32_e32 v94, v94
	v_rcp_f32_e32 v95, v95
	v_pk_mul_f32 v[88:89], v[88:89], v[92:93]
	v_pk_mul_f32 v[80:81], v[80:81], v[240:241] op_sel_hi:[1,0]
	v_pk_mul_f32 v[82:83], v[82:83], v[240:241] op_sel_hi:[1,0]
	v_pk_mul_f32 v[88:89], v[80:81], v[88:89]
	v_pk_mul_f32 v[80:81], v[90:91], v[94:95]
	v_pk_mul_f32 v[76:77], v[76:77], v[162:163] op_sel_hi:[1,0]
	v_pk_mul_f32 v[90:91], v[82:83], v[80:81]
	v_cvt_pk_bf16_f32 v80, v84, v85
	v_mad_i64_i32 v[84:85], s[38:39], v164, s49, v[112:113]
	v_cvt_pk_bf16_f32 v81, v86, v87
	v_cvt_pk_bf16_f32 v82, v88, v89
	v_cvt_pk_bf16_f32 v83, v90, v91
	v_lshl_add_u64 v[84:85], v[84:85], 0, v[114:115]
	v_pk_mul_f32 v[78:79], v[78:79], v[162:163] op_sel_hi:[1,0]
	v_exp_f32_e64 v86, -v76
	v_exp_f32_e64 v87, -v77
	global_store_dwordx4 v[84:85], v[80:83], off
	v_pk_mul_f32 v[68:69], v[68:69], v[242:243] op_sel_hi:[1,0]
	v_pk_mul_f32 v[72:73], v[72:73], v[162:163] op_sel_hi:[1,0]
	v_exp_f32_e64 v82, -v78
	v_exp_f32_e64 v83, -v79
	v_add_f32_e32 v80, 1.0, v86
	v_add_f32_e32 v81, 1.0, v87
	v_rcp_f32_e32 v80, v80
	v_rcp_f32_e32 v81, v81
	v_add_f32_e32 v82, 1.0, v82
	v_add_f32_e32 v83, 1.0, v83
	v_rcp_f32_e32 v82, v82
	v_rcp_f32_e32 v83, v83
	v_pk_mul_f32 v[76:77], v[76:77], v[80:81]
	v_pk_mul_f32 v[70:71], v[70:71], v[242:243] op_sel_hi:[1,0]
	v_pk_mul_f32 v[68:69], v[68:69], v[76:77]
	v_pk_mul_f32 v[76:77], v[78:79], v[82:83]
	v_exp_f32_e64 v78, -v72
	v_exp_f32_e64 v79, -v73
	v_pk_mul_f32 v[74:75], v[74:75], v[162:163] op_sel_hi:[1,0]
	v_pk_mul_f32 v[70:71], v[70:71], v[76:77]
	v_add_f32_e32 v76, 1.0, v78
	v_add_f32_e32 v77, 1.0, v79
	v_exp_f32_e64 v78, -v74
	v_exp_f32_e64 v79, -v75
	v_rcp_f32_e32 v76, v76
	v_rcp_f32_e32 v77, v77
	v_add_f32_e32 v78, 1.0, v78
	v_add_f32_e32 v79, 1.0, v79
	v_rcp_f32_e32 v78, v78
	v_rcp_f32_e32 v79, v79
	v_pk_mul_f32 v[72:73], v[72:73], v[76:77]
	v_pk_mul_f32 v[64:65], v[64:65], v[242:243] op_sel_hi:[1,0]
	v_pk_mul_f32 v[66:67], v[66:67], v[242:243] op_sel_hi:[1,0]
	v_pk_mul_f32 v[72:73], v[64:65], v[72:73]
	v_pk_mul_f32 v[64:65], v[74:75], v[78:79]
	v_pk_mul_f32 v[60:61], v[60:61], v[158:159] op_sel_hi:[1,0]
	v_pk_mul_f32 v[74:75], v[66:67], v[64:65]
	v_cvt_pk_bf16_f32 v64, v68, v69
	v_mad_i64_i32 v[68:69], s[38:39], v160, s49, v[112:113]
	v_cvt_pk_bf16_f32 v65, v70, v71
	v_cvt_pk_bf16_f32 v66, v72, v73
	v_cvt_pk_bf16_f32 v67, v74, v75
	v_lshl_add_u64 v[68:69], v[68:69], 0, v[114:115]
	v_pk_mul_f32 v[62:63], v[62:63], v[158:159] op_sel_hi:[1,0]
	v_exp_f32_e64 v70, -v60
	v_exp_f32_e64 v71, -v61
	global_store_dwordx4 v[68:69], v[64:67], off
	v_pk_mul_f32 v[52:53], v[52:53], v[244:245] op_sel_hi:[1,0]
	v_pk_mul_f32 v[56:57], v[56:57], v[158:159] op_sel_hi:[1,0]
	v_exp_f32_e64 v66, -v62
	v_exp_f32_e64 v67, -v63
	v_add_f32_e32 v64, 1.0, v70
	v_add_f32_e32 v65, 1.0, v71
	v_rcp_f32_e32 v64, v64
	v_rcp_f32_e32 v65, v65
	v_add_f32_e32 v66, 1.0, v66
	v_add_f32_e32 v67, 1.0, v67
	v_rcp_f32_e32 v66, v66
	v_rcp_f32_e32 v67, v67
	v_pk_mul_f32 v[60:61], v[60:61], v[64:65]
	v_pk_mul_f32 v[54:55], v[54:55], v[244:245] op_sel_hi:[1,0]
	v_pk_mul_f32 v[52:53], v[52:53], v[60:61]
	v_pk_mul_f32 v[60:61], v[62:63], v[66:67]
	v_exp_f32_e64 v62, -v56
	v_exp_f32_e64 v63, -v57
	v_pk_mul_f32 v[58:59], v[58:59], v[158:159] op_sel_hi:[1,0]
	v_pk_mul_f32 v[54:55], v[54:55], v[60:61]
	v_add_f32_e32 v60, 1.0, v62
	v_add_f32_e32 v61, 1.0, v63
	v_exp_f32_e64 v62, -v58
	v_exp_f32_e64 v63, -v59
	v_rcp_f32_e32 v60, v60
	v_rcp_f32_e32 v61, v61
	v_add_f32_e32 v62, 1.0, v62
	v_add_f32_e32 v63, 1.0, v63
	v_rcp_f32_e32 v62, v62
	v_rcp_f32_e32 v63, v63
	v_pk_mul_f32 v[56:57], v[56:57], v[60:61]
	v_pk_mul_f32 v[48:49], v[48:49], v[244:245] op_sel_hi:[1,0]
	v_pk_mul_f32 v[50:51], v[50:51], v[244:245] op_sel_hi:[1,0]
	v_pk_mul_f32 v[56:57], v[48:49], v[56:57]
	v_pk_mul_f32 v[48:49], v[58:59], v[62:63]
	v_pk_mul_f32 v[44:45], v[44:45], v[154:155] op_sel_hi:[1,0]
	v_pk_mul_f32 v[58:59], v[50:51], v[48:49]
	v_cvt_pk_bf16_f32 v48, v52, v53
	v_mad_i64_i32 v[52:53], s[38:39], v156, s49, v[112:113]
	v_cvt_pk_bf16_f32 v49, v54, v55
; DI float silu(float x) { return x * sigm(x); }
; DI int lane_id() { int l; asm volatile("v_mbcnt_lo_u32_b32 %0, -1, 0\n\tv_mbcnt_hi_u32_b32 %0, -1, %0" : "=v"(l)); return l; }
; DI u32x4 pack8(f32x4 a, f32x4 b) { u32x4 w; w.x = pk2(a[0], a[1]); w.y = pk2(a[2], a[3]); w.z = pk2(b[0], b[1]); w.w = pk2(b[2], b[3]); return w; }
; #define PG8_BAR __builtin_amdgcn_s_barrier()
; #define EPI_ROWS(ai, m) _Pragma("unroll") for (int ai = 0; ai < 2; ++ai) _Pragma("unroll") for (int m = 0; m < 4; ++m)
; template <class Epi>
; DI void gemm_phase(LAS unsigned char* lds, const int wid, const Gemm g, const Order& S, const Epi& E) {
;     ...
;         if (wr == 0) PG8_BAR;
;         { const int le = lane_id(); E(acc, cur, wr, wc, le & 15, le >> 4); }
;         if (!has_next) break;
; #pragma unroll
;         for (int a = 0; a < 2; ++a)
; #pragma unroll
;             for (int b = 0; b < 2; ++b)
; #pragma unroll
;                 for (int m = 0; m < 4; ++m)
; #pragma unroll
;                     for (int n = 0; n < 2; ++n) acc[a][b][m][n] = (f32x4){0.f, 0.f, 0.f, 0.f};
;         cur = nxt; cA = nA; cB = nB; ++ui;
;         if (wr == 1) PG8_BAR;
;     DI void operator()(const Acc& acc, const Unit& u, int wr, int wc, int fr, int fq) const {
;     ...
;         EPI_ROWS(ai, m) { const int row = epi_row(u, ai, wr, m, fr); const float r = rr[ai][m];
;             f32x4 v[2];
; #pragma unroll
;             for (int n = 0; n < 2; ++n)
; #pragma unroll
;                 for (int j = 0; j < 4; ++j) v[n][j] = silu(acc[ai][0][m][n][j] * r) * (acc[ai][1][m][n][j] * r);
;             *(u32x4*)(act + (size_t)row * FF + cb) = pack8(v[0], v[1]); }
	v_cvt_pk_bf16_f32 v50, v56, v57
	v_cvt_pk_bf16_f32 v51, v58, v59
	v_lshl_add_u64 v[52:53], v[52:53], 0, v[114:115]
	v_pk_mul_f32 v[46:47], v[46:47], v[154:155] op_sel_hi:[1,0]
	v_exp_f32_e64 v54, -v44
	v_exp_f32_e64 v55, -v45
	global_store_dwordx4 v[52:53], v[48:51], off
	v_pk_mul_f32 v[36:37], v[36:37], v[246:247] op_sel_hi:[1,0]
	v_pk_mul_f32 v[40:41], v[40:41], v[154:155] op_sel_hi:[1,0]
	v_exp_f32_e64 v50, -v46
	v_exp_f32_e64 v51, -v47
	v_add_f32_e32 v48, 1.0, v54
	v_add_f32_e32 v49, 1.0, v55
	v_rcp_f32_e32 v48, v48
	v_rcp_f32_e32 v49, v49
	v_add_f32_e32 v50, 1.0, v50
	v_add_f32_e32 v51, 1.0, v51
	v_rcp_f32_e32 v50, v50
	v_rcp_f32_e32 v51, v51
	v_pk_mul_f32 v[44:45], v[44:45], v[48:49]
	v_pk_mul_f32 v[38:39], v[38:39], v[246:247] op_sel_hi:[1,0]
	v_pk_mul_f32 v[36:37], v[36:37], v[44:45]
	v_pk_mul_f32 v[44:45], v[46:47], v[50:51]
	v_exp_f32_e64 v46, -v40
	v_exp_f32_e64 v47, -v41
	v_pk_mul_f32 v[42:43], v[42:43], v[154:155] op_sel_hi:[1,0]
	v_pk_mul_f32 v[38:39], v[38:39], v[44:45]
	v_add_f32_e32 v44, 1.0, v46
	v_add_f32_e32 v45, 1.0, v47
	v_exp_f32_e64 v46, -v42
	v_exp_f32_e64 v47, -v43
	v_rcp_f32_e32 v44, v44
	v_rcp_f32_e32 v45, v45
	v_add_f32_e32 v46, 1.0, v46
	v_add_f32_e32 v47, 1.0, v47
	v_rcp_f32_e32 v46, v46
	v_rcp_f32_e32 v47, v47
	v_pk_mul_f32 v[40:41], v[40:41], v[44:45]
	v_pk_mul_f32 v[32:33], v[32:33], v[246:247] op_sel_hi:[1,0]
	v_pk_mul_f32 v[34:35], v[34:35], v[246:247] op_sel_hi:[1,0]
	v_pk_mul_f32 v[40:41], v[32:33], v[40:41]
	v_pk_mul_f32 v[32:33], v[42:43], v[46:47]
	v_pk_mul_f32 v[28:29], v[28:29], v[150:151] op_sel_hi:[1,0]
	v_pk_mul_f32 v[42:43], v[34:35], v[32:33]
	v_cvt_pk_bf16_f32 v32, v36, v37
	v_mad_i64_i32 v[36:37], s[38:39], v152, s49, v[112:113]
	v_cvt_pk_bf16_f32 v33, v38, v39
	v_cvt_pk_bf16_f32 v34, v40, v41
	v_cvt_pk_bf16_f32 v35, v42, v43
	v_lshl_add_u64 v[36:37], v[36:37], 0, v[114:115]
	v_pk_mul_f32 v[30:31], v[30:31], v[150:151] op_sel_hi:[1,0]
	v_exp_f32_e64 v38, -v28
	v_exp_f32_e64 v39, -v29
	global_store_dwordx4 v[36:37], v[32:35], off
	v_pk_mul_f32 v[20:21], v[20:21], v[248:249] op_sel_hi:[1,0]
	v_pk_mul_f32 v[24:25], v[24:25], v[150:151] op_sel_hi:[1,0]
	v_exp_f32_e64 v34, -v30
	v_exp_f32_e64 v35, -v31
	v_add_f32_e32 v32, 1.0, v38
	v_add_f32_e32 v33, 1.0, v39
	v_rcp_f32_e32 v32, v32
	v_rcp_f32_e32 v33, v33
	v_add_f32_e32 v34, 1.0, v34
	v_add_f32_e32 v35, 1.0, v35
	v_rcp_f32_e32 v34, v34
	v_rcp_f32_e32 v35, v35
	v_pk_mul_f32 v[28:29], v[28:29], v[32:33]
	v_pk_mul_f32 v[22:23], v[22:23], v[248:249] op_sel_hi:[1,0]
	v_pk_mul_f32 v[20:21], v[20:21], v[28:29]
	v_pk_mul_f32 v[28:29], v[30:31], v[34:35]
	v_exp_f32_e64 v30, -v24
	v_exp_f32_e64 v31, -v25
	v_pk_mul_f32 v[26:27], v[26:27], v[150:151] op_sel_hi:[1,0]
	v_pk_mul_f32 v[22:23], v[22:23], v[28:29]
	v_add_f32_e32 v28, 1.0, v30
	v_add_f32_e32 v29, 1.0, v31
	v_exp_f32_e64 v30, -v26
	v_exp_f32_e64 v31, -v27
	v_rcp_f32_e32 v28, v28
	v_rcp_f32_e32 v29, v29
	v_add_f32_e32 v30, 1.0, v30
	v_add_f32_e32 v31, 1.0, v31
	v_rcp_f32_e32 v30, v30
	v_rcp_f32_e32 v31, v31
	v_pk_mul_f32 v[24:25], v[24:25], v[28:29]
	v_pk_mul_f32 v[16:17], v[16:17], v[248:249] op_sel_hi:[1,0]
	v_pk_mul_f32 v[18:19], v[18:19], v[248:249] op_sel_hi:[1,0]
	v_pk_mul_f32 v[24:25], v[16:17], v[24:25]
	v_pk_mul_f32 v[16:17], v[26:27], v[30:31]
	v_pk_mul_f32 v[12:13], v[12:13], v[146:147] op_sel_hi:[1,0]
	v_pk_mul_f32 v[26:27], v[18:19], v[16:17]
	v_cvt_pk_bf16_f32 v16, v20, v21
	v_mad_i64_i32 v[20:21], s[38:39], v148, s49, v[112:113]
	v_cvt_pk_bf16_f32 v17, v22, v23
	v_cvt_pk_bf16_f32 v18, v24, v25
	v_cvt_pk_bf16_f32 v19, v26, v27
	v_lshl_add_u64 v[20:21], v[20:21], 0, v[114:115]
	v_pk_mul_f32 v[14:15], v[14:15], v[146:147] op_sel_hi:[1,0]
	v_exp_f32_e64 v22, -v12
	v_exp_f32_e64 v23, -v13
	global_store_dwordx4 v[20:21], v[16:19], off
	v_pk_mul_f32 v[4:5], v[4:5], v[250:251] op_sel_hi:[1,0]
	v_pk_mul_f32 v[8:9], v[8:9], v[146:147] op_sel_hi:[1,0]
	v_exp_f32_e64 v18, -v14
	v_exp_f32_e64 v19, -v15
	v_add_f32_e32 v16, 1.0, v22
	v_add_f32_e32 v17, 1.0, v23
	v_rcp_f32_e32 v16, v16
	v_rcp_f32_e32 v17, v17
	v_add_f32_e32 v18, 1.0, v18
	v_add_f32_e32 v19, 1.0, v19
	v_rcp_f32_e32 v18, v18
	v_rcp_f32_e32 v19, v19
	v_pk_mul_f32 v[12:13], v[12:13], v[16:17]
	v_pk_mul_f32 v[6:7], v[6:7], v[250:251] op_sel_hi:[1,0]
	v_pk_mul_f32 v[4:5], v[4:5], v[12:13]
	v_pk_mul_f32 v[12:13], v[14:15], v[18:19]
	v_exp_f32_e64 v14, -v8
	v_exp_f32_e64 v15, -v9
	v_pk_mul_f32 v[10:11], v[10:11], v[146:147] op_sel_hi:[1,0]
	v_pk_mul_f32 v[6:7], v[6:7], v[12:13]
	v_add_f32_e32 v12, 1.0, v14
	v_add_f32_e32 v13, 1.0, v15
	v_exp_f32_e64 v14, -v10
	v_exp_f32_e64 v15, -v11
	v_rcp_f32_e32 v12, v12
	v_rcp_f32_e32 v13, v13
	v_add_f32_e32 v14, 1.0, v14
	v_add_f32_e32 v15, 1.0, v15
	v_rcp_f32_e32 v14, v14
	v_rcp_f32_e32 v15, v15
	v_pk_mul_f32 v[8:9], v[8:9], v[12:13]
	v_pk_mul_f32 v[0:1], v[0:1], v[250:251] op_sel_hi:[1,0]
	v_pk_mul_f32 v[2:3], v[2:3], v[250:251] op_sel_hi:[1,0]
	v_pk_mul_f32 v[8:9], v[0:1], v[8:9]
	v_pk_mul_f32 v[0:1], v[10:11], v[14:15]
	s_nop 0
	v_pk_mul_f32 v[10:11], v[2:3], v[0:1]
	v_cvt_pk_bf16_f32 v0, v4, v5
	v_mad_i64_i32 v[4:5], s[38:39], v144, s49, v[112:113]
	v_cvt_pk_bf16_f32 v1, v6, v7
	v_cvt_pk_bf16_f32 v2, v8, v9
	v_cvt_pk_bf16_f32 v3, v10, v11
	v_lshl_add_u64 v[4:5], v[4:5], 0, v[114:115]
	global_store_dwordx4 v[4:5], v[0:3], off
	s_cbranch_vccnz .LBB0_1332
	s_andn2_b64 vcc, exec, s[10:11]
	s_cbranch_vccnz .LBB0_1331
	s_barrier
	s_branch .LBB0_1331
